# v059 + branch-GEMM gate epilogue rewritten by hand: rolling pipeline over the 8 row granules (4 granules of gate/partial loads in flight while earlier ones are computed and stored), scalar-base addres
# baseline (speedup 1.0000x reference)
; #define LAS __attribute__((address_space(3)))
; __device__ __forceinline__ unsigned pk2(float lo, float hi) { f32x2 v = {lo, hi}; bf16x2_t b = __builtin_convertvector(v, bf16x2_t); return __builtin_bit_cast(unsigned, b); }
; __device__ __forceinline__ float bflo(unsigned w) { return __uint_as_float(w << 16); }
; __device__ __forceinline__ float bfhi(unsigned w) { return __uint_as_float(w & 0xffff0000u); }
;     __device__ __forceinline__ void operator()(const f32x4 (&acc)[2][2][4][2], const Unit& u, int wr, int wc, int fr, int fq, LAS unsigned char* lds, int tid) const {
;         const int row0 = u.pm * BM + wr * 64 + fr, col0 = u.pn * BM + wc * 32 + 8 * fq;
;         const int pz = u.pz;
;         gbf16* dst = (pz == 2) ? merged : part;
; #pragma unroll
;         for (int ai = 0; ai < 2; ++ai) {
;             u32x4 gv[4][2], pv[4][2];
; #pragma unroll
;             for (int m = 0; m < 4; ++m) { const size_t row = (size_t)(row0 + ai * HALF + m * 16);
; #pragma unroll
;                 for (int bj = 0; bj < 2; ++bj) { const int col = col0 + bj * HALF;
;                     gv[m][bj] = *(const gu32x4*)(proj + row * PROJ + 2048 + 1024 * pz + col);
;                     if (pz != 0) pv[m][bj] = *(const gu32x4*)(part + row * DM + col); else pv[m][bj] = (u32x4){0u, 0u, 0u, 0u}; } }
;             asm volatile("" ::: "memory");
; #pragma unroll
;             for (int m = 0; m < 4; ++m) { const size_t row = (size_t)(row0 + ai * HALF + m * 16);
; #pragma unroll
;                 for (int bj = 0; bj < 2; ++bj) { const int col = col0 + bj * HALF; const u32x4 gw = gv[m][bj], pw = pv[m][bj];
;                     f32x4 z0, z1;
;                     z0[0] = sigmoidf_(bflo(gw.x)); z0[1] = sigmoidf_(bfhi(gw.x)); z0[2] = sigmoidf_(bflo(gw.y)); z0[3] = sigmoidf_(bfhi(gw.y));
;                     z1[0] = sigmoidf_(bflo(gw.z)); z1[1] = sigmoidf_(bfhi(gw.z)); z1[2] = sigmoidf_(bflo(gw.w)); z1[3] = sigmoidf_(bfhi(gw.w));
;                     const f32x4 q0 = {bflo(pw.x), bfhi(pw.x), bflo(pw.y), bfhi(pw.y)}, q1 = {bflo(pw.z), bfhi(pw.z), bflo(pw.w), bfhi(pw.w)};
;                     z0 = z0 * acc[ai][bj][m][0] + q0; z1 = z1 * acc[ai][bj][m][1] + q1;
;                     u32x4 w; w.x = pk2(z0[0], z0[1]); w.y = pk2(z0[2], z0[3]); w.z = pk2(z1[0], z1[1]); w.w = pk2(z1[2], z1[3]);
;                     *(gu32x4*)(dst + row * DM + col) = w; } }
.LBB0_447:
	s_mul_i32 vcc_lo, s0, 0x280000
	s_lshl_b32 vcc_hi, s4, 9
	s_lshl_b32 s16, s0, 19
	s_add_u32 s16, s16, vcc_hi
	s_add_u32 vcc_lo, vcc_lo, vcc_hi
	s_lshl_b32 vcc_hi, s12, 11
	s_add_u32 vcc_lo, vcc_lo, vcc_hi
	s_add_u32 vcc_lo, vcc_lo, 0x1000
	s_add_u32 s0, s96, vcc_lo
	s_addc_u32 s1, s97, 0
	s_add_u32 s4, s8, s16
	s_addc_u32 s5, s9, 0
	s_cmp_eq_u32 s12, 2
	s_cselect_b32 vcc_lo, s64, s8
	s_cselect_b32 vcc_hi, s41, s9
	s_add_u32 s16, vcc_lo, s16
	s_addc_u32 s17, vcc_hi, 0
	v_mul_u32_u24_e32 v122, 0x2800, v241
	v_lshl_add_u32 v122, v243, 1, v122
	v_lshlrev_b32_e32 v123, 11, v241
	v_lshl_add_u32 v123, v243, 1, v123
	s_cmp_eq_u32 s12, 0
	s_cbranch_scc1 .Lgate_pz0
	global_load_dwordx4 v[132:135], v122, s[0:1]
	global_load_dwordx4 v[136:139], v122, s[0:1] offset:256
	global_load_dwordx4 v[140:143], v123, s[4:5]
	global_load_dwordx4 v[144:147], v123, s[4:5] offset:256
	s_add_u32 s0, s0, 0x28000
	s_addc_u32 s1, s1, 0
	s_add_u32 s4, s4, 0x8000
	s_addc_u32 s5, s5, 0
	global_load_dwordx4 v[148:151], v122, s[0:1]
	global_load_dwordx4 v[152:155], v122, s[0:1] offset:256
	global_load_dwordx4 v[156:159], v123, s[4:5]
	global_load_dwordx4 v[160:163], v123, s[4:5] offset:256
	s_add_u32 s0, s0, 0x28000
	s_addc_u32 s1, s1, 0
	s_add_u32 s4, s4, 0x8000
	s_addc_u32 s5, s5, 0
	global_load_dwordx4 v[164:167], v122, s[0:1]
	global_load_dwordx4 v[168:171], v122, s[0:1] offset:256
	global_load_dwordx4 v[172:175], v123, s[4:5]
	global_load_dwordx4 v[176:179], v123, s[4:5] offset:256
	s_add_u32 s0, s0, 0x28000
	s_addc_u32 s1, s1, 0
	s_add_u32 s4, s4, 0x8000
	s_addc_u32 s5, s5, 0
	global_load_dwordx4 v[180:183], v122, s[0:1]
	global_load_dwordx4 v[184:187], v122, s[0:1] offset:256
	global_load_dwordx4 v[188:191], v123, s[4:5]
	global_load_dwordx4 v[192:195], v123, s[4:5] offset:256
	s_add_u32 s0, s0, 0xc8000
	s_addc_u32 s1, s1, 0
	s_add_u32 s4, s4, 0x28000
	s_addc_u32 s5, s5, 0
	s_waitcnt vmcnt(12)
	v_lshlrev_b32_e32 v214, 16, v132
	v_and_b32_e32 v215, 0xffff0000, v132
	v_lshlrev_b32_e32 v216, 16, v133
	v_and_b32_e32 v217, 0xffff0000, v133
	v_lshlrev_b32_e32 v218, 16, v134
	v_and_b32_e32 v219, 0xffff0000, v134
	v_lshlrev_b32_e32 v220, 16, v135
	v_and_b32_e32 v221, 0xffff0000, v135
	v_mul_f32_e32 v214, 0xbfb8aa3b, v214
	v_mul_f32_e32 v215, 0xbfb8aa3b, v215
	v_mul_f32_e32 v216, 0xbfb8aa3b, v216
	v_mul_f32_e32 v217, 0xbfb8aa3b, v217
	v_mul_f32_e32 v218, 0xbfb8aa3b, v218
	v_mul_f32_e32 v219, 0xbfb8aa3b, v219
	v_mul_f32_e32 v220, 0xbfb8aa3b, v220
	v_mul_f32_e32 v221, 0xbfb8aa3b, v221
	v_exp_f32_e32 v214, v214
	v_exp_f32_e32 v215, v215
	v_exp_f32_e32 v216, v216
	v_exp_f32_e32 v217, v217
	v_exp_f32_e32 v218, v218
	v_exp_f32_e32 v219, v219
	v_exp_f32_e32 v220, v220
	v_exp_f32_e32 v221, v221
	v_add_f32_e32 v214, 1.0, v214
	v_add_f32_e32 v215, 1.0, v215
	v_add_f32_e32 v216, 1.0, v216
	v_add_f32_e32 v217, 1.0, v217
	v_add_f32_e32 v218, 1.0, v218
	v_add_f32_e32 v219, 1.0, v219
	v_add_f32_e32 v220, 1.0, v220
	v_add_f32_e32 v221, 1.0, v221
	v_rcp_f32_e32 v214, v214
	v_rcp_f32_e32 v215, v215
	v_rcp_f32_e32 v216, v216
	v_rcp_f32_e32 v217, v217
	v_rcp_f32_e32 v218, v218
	v_rcp_f32_e32 v219, v219
	v_rcp_f32_e32 v220, v220
	v_rcp_f32_e32 v221, v221
	v_lshlrev_b32_e32 v222, 16, v140
	v_and_b32_e32 v223, 0xffff0000, v140
	v_pk_fma_f32 v[128:129], v[128:129], v[214:215], v[222:223]
	v_lshlrev_b32_e32 v222, 16, v141
	v_and_b32_e32 v223, 0xffff0000, v141
	v_pk_fma_f32 v[130:131], v[130:131], v[216:217], v[222:223]
	v_lshlrev_b32_e32 v222, 16, v142
	v_and_b32_e32 v223, 0xffff0000, v142
	v_pk_fma_f32 v[124:125], v[124:125], v[218:219], v[222:223]
	v_lshlrev_b32_e32 v222, 16, v143
	v_and_b32_e32 v223, 0xffff0000, v143
	v_pk_fma_f32 v[126:127], v[126:127], v[220:221], v[222:223]
	v_cvt_pk_bf16_f32 v132, v128, v129
	v_cvt_pk_bf16_f32 v133, v130, v131
	v_cvt_pk_bf16_f32 v134, v124, v125
	v_cvt_pk_bf16_f32 v135, v126, v127
	v_lshlrev_b32_e32 v214, 16, v136
	v_and_b32_e32 v215, 0xffff0000, v136
	v_lshlrev_b32_e32 v216, 16, v137
	v_and_b32_e32 v217, 0xffff0000, v137
	v_lshlrev_b32_e32 v218, 16, v138
	v_and_b32_e32 v219, 0xffff0000, v138
	v_lshlrev_b32_e32 v220, 16, v139
	v_and_b32_e32 v221, 0xffff0000, v139
	v_mul_f32_e32 v214, 0xbfb8aa3b, v214
	v_mul_f32_e32 v215, 0xbfb8aa3b, v215
	v_mul_f32_e32 v216, 0xbfb8aa3b, v216
	v_mul_f32_e32 v217, 0xbfb8aa3b, v217
	v_mul_f32_e32 v218, 0xbfb8aa3b, v218
	v_mul_f32_e32 v219, 0xbfb8aa3b, v219
	v_mul_f32_e32 v220, 0xbfb8aa3b, v220
	v_mul_f32_e32 v221, 0xbfb8aa3b, v221
	v_exp_f32_e32 v214, v214
	v_exp_f32_e32 v215, v215
	v_exp_f32_e32 v216, v216
	v_exp_f32_e32 v217, v217
	v_exp_f32_e32 v218, v218
	v_exp_f32_e32 v219, v219
	v_exp_f32_e32 v220, v220
	v_exp_f32_e32 v221, v221
	v_add_f32_e32 v214, 1.0, v214
	v_add_f32_e32 v215, 1.0, v215
	v_add_f32_e32 v216, 1.0, v216
	v_add_f32_e32 v217, 1.0, v217
	v_add_f32_e32 v218, 1.0, v218
	v_add_f32_e32 v219, 1.0, v219
	v_add_f32_e32 v220, 1.0, v220
	v_add_f32_e32 v221, 1.0, v221
	v_rcp_f32_e32 v214, v214
	v_rcp_f32_e32 v215, v215
	v_rcp_f32_e32 v216, v216
	v_rcp_f32_e32 v217, v217
	v_rcp_f32_e32 v218, v218
	v_rcp_f32_e32 v219, v219
	v_rcp_f32_e32 v220, v220
	v_rcp_f32_e32 v221, v221
	v_lshlrev_b32_e32 v222, 16, v144
	v_and_b32_e32 v223, 0xffff0000, v144
	v_pk_fma_f32 v[118:119], v[118:119], v[214:215], v[222:223]
	v_lshlrev_b32_e32 v222, 16, v145
	v_and_b32_e32 v223, 0xffff0000, v145
	v_pk_fma_f32 v[120:121], v[120:121], v[216:217], v[222:223]
	v_lshlrev_b32_e32 v222, 16, v146
	v_and_b32_e32 v223, 0xffff0000, v146
	v_pk_fma_f32 v[114:115], v[114:115], v[218:219], v[222:223]
	v_lshlrev_b32_e32 v222, 16, v147
	v_and_b32_e32 v223, 0xffff0000, v147
	v_pk_fma_f32 v[116:117], v[116:117], v[220:221], v[222:223]
	v_cvt_pk_bf16_f32 v136, v118, v119
	v_cvt_pk_bf16_f32 v137, v120, v121
	v_cvt_pk_bf16_f32 v138, v114, v115
	v_cvt_pk_bf16_f32 v139, v116, v117
	global_store_dwordx4 v123, v[132:135], s[16:17]
	global_store_dwordx4 v123, v[136:139], s[16:17] offset:256
	s_add_u32 s16, s16, 0x8000
	s_addc_u32 s17, s17, 0
	global_load_dwordx4 v[132:135], v122, s[0:1]
	global_load_dwordx4 v[136:139], v122, s[0:1] offset:256
	global_load_dwordx4 v[140:143], v123, s[4:5]
	global_load_dwordx4 v[144:147], v123, s[4:5] offset:256
	s_add_u32 s0, s0, 0x28000
	s_addc_u32 s1, s1, 0
	s_add_u32 s4, s4, 0x8000
	s_addc_u32 s5, s5, 0
	s_waitcnt vmcnt(14)
; __device__ __forceinline__ unsigned pk2(float lo, float hi) { f32x2 v = {lo, hi}; bf16x2_t b = __builtin_convertvector(v, bf16x2_t); return __builtin_bit_cast(unsigned, b); }
; __device__ __forceinline__ float bflo(unsigned w) { return __uint_as_float(w << 16); }
; __device__ __forceinline__ float bfhi(unsigned w) { return __uint_as_float(w & 0xffff0000u); }
; __device__ __forceinline__ float sigmoidf_(float x) { return __builtin_amdgcn_rcpf(1.0f + __builtin_amdgcn_exp2f(-x * LOG2E)); }
;     __device__ __forceinline__ void operator()(const f32x4 (&acc)[2][2][4][2], const Unit& u, int wr, int wc, int fr, int fq, LAS unsigned char* lds, int tid) const {
;     ...
;             for (int m = 0; m < 4; ++m) { const size_t row = (size_t)(row0 + ai * HALF + m * 16);
; #pragma unroll
;                 for (int bj = 0; bj < 2; ++bj) { const int col = col0 + bj * HALF;
;                     gv[m][bj] = *(const gu32x4*)(proj + row * PROJ + 2048 + 1024 * pz + col);
;                     if (pz != 0) pv[m][bj] = *(const gu32x4*)(part + row * DM + col); else pv[m][bj] = (u32x4){0u, 0u, 0u, 0u}; } }
;             asm volatile("" ::: "memory");
; #pragma unroll
;             for (int m = 0; m < 4; ++m) { const size_t row = (size_t)(row0 + ai * HALF + m * 16);
; #pragma unroll
;                 for (int bj = 0; bj < 2; ++bj) { const int col = col0 + bj * HALF; const u32x4 gw = gv[m][bj], pw = pv[m][bj];
;                     f32x4 z0, z1;
;                     z0[0] = sigmoidf_(bflo(gw.x)); z0[1] = sigmoidf_(bfhi(gw.x)); z0[2] = sigmoidf_(bflo(gw.y)); z0[3] = sigmoidf_(bfhi(gw.y));
;                     z1[0] = sigmoidf_(bflo(gw.z)); z1[1] = sigmoidf_(bfhi(gw.z)); z1[2] = sigmoidf_(bflo(gw.w)); z1[3] = sigmoidf_(bfhi(gw.w));
;                     const f32x4 q0 = {bflo(pw.x), bfhi(pw.x), bflo(pw.y), bfhi(pw.y)}, q1 = {bflo(pw.z), bfhi(pw.z), bflo(pw.w), bfhi(pw.w)};
;                     z0 = z0 * acc[ai][bj][m][0] + q0; z1 = z1 * acc[ai][bj][m][1] + q1;
;                     u32x4 w; w.x = pk2(z0[0], z0[1]); w.y = pk2(z0[2], z0[3]); w.z = pk2(z1[0], z1[1]); w.w = pk2(z1[2], z1[3]);
;                     *(gu32x4*)(dst + row * DM + col) = w; } }
	v_lshlrev_b32_e32 v214, 16, v148
	v_and_b32_e32 v215, 0xffff0000, v148
	v_lshlrev_b32_e32 v216, 16, v149
	v_and_b32_e32 v217, 0xffff0000, v149
	v_lshlrev_b32_e32 v218, 16, v150
	v_and_b32_e32 v219, 0xffff0000, v150
	v_lshlrev_b32_e32 v220, 16, v151
	v_and_b32_e32 v221, 0xffff0000, v151
	v_mul_f32_e32 v214, 0xbfb8aa3b, v214
	v_mul_f32_e32 v215, 0xbfb8aa3b, v215
	v_mul_f32_e32 v216, 0xbfb8aa3b, v216
	v_mul_f32_e32 v217, 0xbfb8aa3b, v217
	v_mul_f32_e32 v218, 0xbfb8aa3b, v218
	v_mul_f32_e32 v219, 0xbfb8aa3b, v219
	v_mul_f32_e32 v220, 0xbfb8aa3b, v220
	v_mul_f32_e32 v221, 0xbfb8aa3b, v221
	v_exp_f32_e32 v214, v214
	v_exp_f32_e32 v215, v215
	v_exp_f32_e32 v216, v216
	v_exp_f32_e32 v217, v217
	v_exp_f32_e32 v218, v218
	v_exp_f32_e32 v219, v219
	v_exp_f32_e32 v220, v220
	v_exp_f32_e32 v221, v221
	v_add_f32_e32 v214, 1.0, v214
	v_add_f32_e32 v215, 1.0, v215
	v_add_f32_e32 v216, 1.0, v216
	v_add_f32_e32 v217, 1.0, v217
	v_add_f32_e32 v218, 1.0, v218
	v_add_f32_e32 v219, 1.0, v219
	v_add_f32_e32 v220, 1.0, v220
	v_add_f32_e32 v221, 1.0, v221
	v_rcp_f32_e32 v214, v214
	v_rcp_f32_e32 v215, v215
	v_rcp_f32_e32 v216, v216
	v_rcp_f32_e32 v217, v217
	v_rcp_f32_e32 v218, v218
	v_rcp_f32_e32 v219, v219
	v_rcp_f32_e32 v220, v220
	v_rcp_f32_e32 v221, v221
	v_lshlrev_b32_e32 v222, 16, v156
	v_and_b32_e32 v223, 0xffff0000, v156
	v_pk_fma_f32 v[110:111], v[110:111], v[214:215], v[222:223]
	v_lshlrev_b32_e32 v222, 16, v157
	v_and_b32_e32 v223, 0xffff0000, v157
	v_pk_fma_f32 v[112:113], v[112:113], v[216:217], v[222:223]
	v_lshlrev_b32_e32 v222, 16, v158
	v_and_b32_e32 v223, 0xffff0000, v158
	v_pk_fma_f32 v[106:107], v[106:107], v[218:219], v[222:223]
	v_lshlrev_b32_e32 v222, 16, v159
	v_and_b32_e32 v223, 0xffff0000, v159
	v_pk_fma_f32 v[108:109], v[108:109], v[220:221], v[222:223]
	v_cvt_pk_bf16_f32 v148, v110, v111
	v_cvt_pk_bf16_f32 v149, v112, v113
	v_cvt_pk_bf16_f32 v150, v106, v107
	v_cvt_pk_bf16_f32 v151, v108, v109
	v_lshlrev_b32_e32 v214, 16, v152
	v_and_b32_e32 v215, 0xffff0000, v152
	v_lshlrev_b32_e32 v216, 16, v153
	v_and_b32_e32 v217, 0xffff0000, v153
	v_lshlrev_b32_e32 v218, 16, v154
	v_and_b32_e32 v219, 0xffff0000, v154
	v_lshlrev_b32_e32 v220, 16, v155
	v_and_b32_e32 v221, 0xffff0000, v155
	v_mul_f32_e32 v214, 0xbfb8aa3b, v214
	v_mul_f32_e32 v215, 0xbfb8aa3b, v215
	v_mul_f32_e32 v216, 0xbfb8aa3b, v216
	v_mul_f32_e32 v217, 0xbfb8aa3b, v217
	v_mul_f32_e32 v218, 0xbfb8aa3b, v218
	v_mul_f32_e32 v219, 0xbfb8aa3b, v219
	v_mul_f32_e32 v220, 0xbfb8aa3b, v220
	v_mul_f32_e32 v221, 0xbfb8aa3b, v221
	v_exp_f32_e32 v214, v214
	v_exp_f32_e32 v215, v215
	v_exp_f32_e32 v216, v216
	v_exp_f32_e32 v217, v217
	v_exp_f32_e32 v218, v218
	v_exp_f32_e32 v219, v219
	v_exp_f32_e32 v220, v220
	v_exp_f32_e32 v221, v221
	v_add_f32_e32 v214, 1.0, v214
	v_add_f32_e32 v215, 1.0, v215
	v_add_f32_e32 v216, 1.0, v216
	v_add_f32_e32 v217, 1.0, v217
	v_add_f32_e32 v218, 1.0, v218
	v_add_f32_e32 v219, 1.0, v219
	v_add_f32_e32 v220, 1.0, v220
	v_add_f32_e32 v221, 1.0, v221
	v_rcp_f32_e32 v214, v214
	v_rcp_f32_e32 v215, v215
	v_rcp_f32_e32 v216, v216
	v_rcp_f32_e32 v217, v217
	v_rcp_f32_e32 v218, v218
	v_rcp_f32_e32 v219, v219
	v_rcp_f32_e32 v220, v220
	v_rcp_f32_e32 v221, v221
	v_lshlrev_b32_e32 v222, 16, v160
	v_and_b32_e32 v223, 0xffff0000, v160
	v_pk_fma_f32 v[102:103], v[102:103], v[214:215], v[222:223]
	v_lshlrev_b32_e32 v222, 16, v161
	v_and_b32_e32 v223, 0xffff0000, v161
	v_pk_fma_f32 v[104:105], v[104:105], v[216:217], v[222:223]
	v_lshlrev_b32_e32 v222, 16, v162
	v_and_b32_e32 v223, 0xffff0000, v162
	v_pk_fma_f32 v[98:99], v[98:99], v[218:219], v[222:223]
	v_lshlrev_b32_e32 v222, 16, v163
	v_and_b32_e32 v223, 0xffff0000, v163
	v_pk_fma_f32 v[100:101], v[100:101], v[220:221], v[222:223]
	v_cvt_pk_bf16_f32 v152, v102, v103
	v_cvt_pk_bf16_f32 v153, v104, v105
	v_cvt_pk_bf16_f32 v154, v98, v99
	v_cvt_pk_bf16_f32 v155, v100, v101
	global_store_dwordx4 v123, v[148:151], s[16:17]
	global_store_dwordx4 v123, v[152:155], s[16:17] offset:256
	s_add_u32 s16, s16, 0x8000
	s_addc_u32 s17, s17, 0
	global_load_dwordx4 v[148:151], v122, s[0:1]
	global_load_dwordx4 v[152:155], v122, s[0:1] offset:256
	global_load_dwordx4 v[156:159], v123, s[4:5]
	global_load_dwordx4 v[160:163], v123, s[4:5] offset:256
	s_add_u32 s0, s0, 0x28000
	s_addc_u32 s1, s1, 0
	s_add_u32 s4, s4, 0x8000
	s_addc_u32 s5, s5, 0
	s_waitcnt vmcnt(16)
; __device__ __forceinline__ unsigned pk2(float lo, float hi) { f32x2 v = {lo, hi}; bf16x2_t b = __builtin_convertvector(v, bf16x2_t); return __builtin_bit_cast(unsigned, b); }
; __device__ __forceinline__ float bflo(unsigned w) { return __uint_as_float(w << 16); }
; __device__ __forceinline__ float bfhi(unsigned w) { return __uint_as_float(w & 0xffff0000u); }
; __device__ __forceinline__ float sigmoidf_(float x) { return __builtin_amdgcn_rcpf(1.0f + __builtin_amdgcn_exp2f(-x * LOG2E)); }
;     __device__ __forceinline__ void operator()(const f32x4 (&acc)[2][2][4][2], const Unit& u, int wr, int wc, int fr, int fq, LAS unsigned char* lds, int tid) const {
;     ...
;             for (int m = 0; m < 4; ++m) { const size_t row = (size_t)(row0 + ai * HALF + m * 16);
; #pragma unroll
;                 for (int bj = 0; bj < 2; ++bj) { const int col = col0 + bj * HALF;
;                     gv[m][bj] = *(const gu32x4*)(proj + row * PROJ + 2048 + 1024 * pz + col);
;                     if (pz != 0) pv[m][bj] = *(const gu32x4*)(part + row * DM + col); else pv[m][bj] = (u32x4){0u, 0u, 0u, 0u}; } }
;             asm volatile("" ::: "memory");
; #pragma unroll
;             for (int m = 0; m < 4; ++m) { const size_t row = (size_t)(row0 + ai * HALF + m * 16);
; #pragma unroll
;                 for (int bj = 0; bj < 2; ++bj) { const int col = col0 + bj * HALF; const u32x4 gw = gv[m][bj], pw = pv[m][bj];
;                     f32x4 z0, z1;
;                     z0[0] = sigmoidf_(bflo(gw.x)); z0[1] = sigmoidf_(bfhi(gw.x)); z0[2] = sigmoidf_(bflo(gw.y)); z0[3] = sigmoidf_(bfhi(gw.y));
;                     z1[0] = sigmoidf_(bflo(gw.z)); z1[1] = sigmoidf_(bfhi(gw.z)); z1[2] = sigmoidf_(bflo(gw.w)); z1[3] = sigmoidf_(bfhi(gw.w));
;                     const f32x4 q0 = {bflo(pw.x), bfhi(pw.x), bflo(pw.y), bfhi(pw.y)}, q1 = {bflo(pw.z), bfhi(pw.z), bflo(pw.w), bfhi(pw.w)};
;                     z0 = z0 * acc[ai][bj][m][0] + q0; z1 = z1 * acc[ai][bj][m][1] + q1;
;                     u32x4 w; w.x = pk2(z0[0], z0[1]); w.y = pk2(z0[2], z0[3]); w.z = pk2(z1[0], z1[1]); w.w = pk2(z1[2], z1[3]);
;                     *(gu32x4*)(dst + row * DM + col) = w; } }
	v_lshlrev_b32_e32 v214, 16, v164
	v_and_b32_e32 v215, 0xffff0000, v164
	v_lshlrev_b32_e32 v216, 16, v165
	v_and_b32_e32 v217, 0xffff0000, v165
	v_lshlrev_b32_e32 v218, 16, v166
	v_and_b32_e32 v219, 0xffff0000, v166
	v_lshlrev_b32_e32 v220, 16, v167
	v_and_b32_e32 v221, 0xffff0000, v167
	v_mul_f32_e32 v214, 0xbfb8aa3b, v214
	v_mul_f32_e32 v215, 0xbfb8aa3b, v215
	v_mul_f32_e32 v216, 0xbfb8aa3b, v216
	v_mul_f32_e32 v217, 0xbfb8aa3b, v217
	v_mul_f32_e32 v218, 0xbfb8aa3b, v218
	v_mul_f32_e32 v219, 0xbfb8aa3b, v219
	v_mul_f32_e32 v220, 0xbfb8aa3b, v220
	v_mul_f32_e32 v221, 0xbfb8aa3b, v221
	v_exp_f32_e32 v214, v214
	v_exp_f32_e32 v215, v215
	v_exp_f32_e32 v216, v216
	v_exp_f32_e32 v217, v217
	v_exp_f32_e32 v218, v218
	v_exp_f32_e32 v219, v219
	v_exp_f32_e32 v220, v220
	v_exp_f32_e32 v221, v221
	v_add_f32_e32 v214, 1.0, v214
	v_add_f32_e32 v215, 1.0, v215
	v_add_f32_e32 v216, 1.0, v216
	v_add_f32_e32 v217, 1.0, v217
	v_add_f32_e32 v218, 1.0, v218
	v_add_f32_e32 v219, 1.0, v219
	v_add_f32_e32 v220, 1.0, v220
	v_add_f32_e32 v221, 1.0, v221
	v_rcp_f32_e32 v214, v214
	v_rcp_f32_e32 v215, v215
	v_rcp_f32_e32 v216, v216
	v_rcp_f32_e32 v217, v217
	v_rcp_f32_e32 v218, v218
	v_rcp_f32_e32 v219, v219
	v_rcp_f32_e32 v220, v220
	v_rcp_f32_e32 v221, v221
	v_lshlrev_b32_e32 v222, 16, v172
	v_and_b32_e32 v223, 0xffff0000, v172
	v_pk_fma_f32 v[94:95], v[94:95], v[214:215], v[222:223]
	v_lshlrev_b32_e32 v222, 16, v173
	v_and_b32_e32 v223, 0xffff0000, v173
	v_pk_fma_f32 v[96:97], v[96:97], v[216:217], v[222:223]
	v_lshlrev_b32_e32 v222, 16, v174
	v_and_b32_e32 v223, 0xffff0000, v174
	v_pk_fma_f32 v[90:91], v[90:91], v[218:219], v[222:223]
	v_lshlrev_b32_e32 v222, 16, v175
	v_and_b32_e32 v223, 0xffff0000, v175
	v_pk_fma_f32 v[92:93], v[92:93], v[220:221], v[222:223]
	v_cvt_pk_bf16_f32 v164, v94, v95
	v_cvt_pk_bf16_f32 v165, v96, v97
	v_cvt_pk_bf16_f32 v166, v90, v91
	v_cvt_pk_bf16_f32 v167, v92, v93
	v_lshlrev_b32_e32 v214, 16, v168
	v_and_b32_e32 v215, 0xffff0000, v168
	v_lshlrev_b32_e32 v216, 16, v169
	v_and_b32_e32 v217, 0xffff0000, v169
	v_lshlrev_b32_e32 v218, 16, v170
	v_and_b32_e32 v219, 0xffff0000, v170
	v_lshlrev_b32_e32 v220, 16, v171
	v_and_b32_e32 v221, 0xffff0000, v171
	v_mul_f32_e32 v214, 0xbfb8aa3b, v214
	v_mul_f32_e32 v215, 0xbfb8aa3b, v215
	v_mul_f32_e32 v216, 0xbfb8aa3b, v216
	v_mul_f32_e32 v217, 0xbfb8aa3b, v217
	v_mul_f32_e32 v218, 0xbfb8aa3b, v218
	v_mul_f32_e32 v219, 0xbfb8aa3b, v219
	v_mul_f32_e32 v220, 0xbfb8aa3b, v220
	v_mul_f32_e32 v221, 0xbfb8aa3b, v221
	v_exp_f32_e32 v214, v214
	v_exp_f32_e32 v215, v215
	v_exp_f32_e32 v216, v216
	v_exp_f32_e32 v217, v217
	v_exp_f32_e32 v218, v218
	v_exp_f32_e32 v219, v219
	v_exp_f32_e32 v220, v220
	v_exp_f32_e32 v221, v221
	v_add_f32_e32 v214, 1.0, v214
	v_add_f32_e32 v215, 1.0, v215
	v_add_f32_e32 v216, 1.0, v216
	v_add_f32_e32 v217, 1.0, v217
	v_add_f32_e32 v218, 1.0, v218
	v_add_f32_e32 v219, 1.0, v219
	v_add_f32_e32 v220, 1.0, v220
	v_add_f32_e32 v221, 1.0, v221
	v_rcp_f32_e32 v214, v214
	v_rcp_f32_e32 v215, v215
	v_rcp_f32_e32 v216, v216
	v_rcp_f32_e32 v217, v217
	v_rcp_f32_e32 v218, v218
	v_rcp_f32_e32 v219, v219
	v_rcp_f32_e32 v220, v220
	v_rcp_f32_e32 v221, v221
	v_lshlrev_b32_e32 v222, 16, v176
	v_and_b32_e32 v223, 0xffff0000, v176
	v_pk_fma_f32 v[86:87], v[86:87], v[214:215], v[222:223]
	v_lshlrev_b32_e32 v222, 16, v177
	v_and_b32_e32 v223, 0xffff0000, v177
	v_pk_fma_f32 v[88:89], v[88:89], v[216:217], v[222:223]
	v_lshlrev_b32_e32 v222, 16, v178
	v_and_b32_e32 v223, 0xffff0000, v178
	v_pk_fma_f32 v[82:83], v[82:83], v[218:219], v[222:223]
	v_lshlrev_b32_e32 v222, 16, v179
	v_and_b32_e32 v223, 0xffff0000, v179
	v_pk_fma_f32 v[84:85], v[84:85], v[220:221], v[222:223]
	v_cvt_pk_bf16_f32 v168, v86, v87
	v_cvt_pk_bf16_f32 v169, v88, v89
	v_cvt_pk_bf16_f32 v170, v82, v83
	v_cvt_pk_bf16_f32 v171, v84, v85
	global_store_dwordx4 v123, v[164:167], s[16:17]
	global_store_dwordx4 v123, v[168:171], s[16:17] offset:256
	s_add_u32 s16, s16, 0x8000
	s_addc_u32 s17, s17, 0
	global_load_dwordx4 v[164:167], v122, s[0:1]
	global_load_dwordx4 v[168:171], v122, s[0:1] offset:256
	global_load_dwordx4 v[172:175], v123, s[4:5]
	global_load_dwordx4 v[176:179], v123, s[4:5] offset:256
	s_add_u32 s0, s0, 0x28000
	s_addc_u32 s1, s1, 0
	s_add_u32 s4, s4, 0x8000
	s_addc_u32 s5, s5, 0
	s_waitcnt vmcnt(18)
; __device__ __forceinline__ unsigned pk2(float lo, float hi) { f32x2 v = {lo, hi}; bf16x2_t b = __builtin_convertvector(v, bf16x2_t); return __builtin_bit_cast(unsigned, b); }
; __device__ __forceinline__ float bflo(unsigned w) { return __uint_as_float(w << 16); }
; __device__ __forceinline__ float bfhi(unsigned w) { return __uint_as_float(w & 0xffff0000u); }
; __device__ __forceinline__ float sigmoidf_(float x) { return __builtin_amdgcn_rcpf(1.0f + __builtin_amdgcn_exp2f(-x * LOG2E)); }
;     __device__ __forceinline__ void operator()(const f32x4 (&acc)[2][2][4][2], const Unit& u, int wr, int wc, int fr, int fq, LAS unsigned char* lds, int tid) const {
;     ...
;             for (int m = 0; m < 4; ++m) { const size_t row = (size_t)(row0 + ai * HALF + m * 16);
; #pragma unroll
;                 for (int bj = 0; bj < 2; ++bj) { const int col = col0 + bj * HALF;
;                     gv[m][bj] = *(const gu32x4*)(proj + row * PROJ + 2048 + 1024 * pz + col);
;                     if (pz != 0) pv[m][bj] = *(const gu32x4*)(part + row * DM + col); else pv[m][bj] = (u32x4){0u, 0u, 0u, 0u}; } }
;             asm volatile("" ::: "memory");
; #pragma unroll
;             for (int m = 0; m < 4; ++m) { const size_t row = (size_t)(row0 + ai * HALF + m * 16);
; #pragma unroll
;                 for (int bj = 0; bj < 2; ++bj) { const int col = col0 + bj * HALF; const u32x4 gw = gv[m][bj], pw = pv[m][bj];
;                     f32x4 z0, z1;
;                     z0[0] = sigmoidf_(bflo(gw.x)); z0[1] = sigmoidf_(bfhi(gw.x)); z0[2] = sigmoidf_(bflo(gw.y)); z0[3] = sigmoidf_(bfhi(gw.y));
;                     z1[0] = sigmoidf_(bflo(gw.z)); z1[1] = sigmoidf_(bfhi(gw.z)); z1[2] = sigmoidf_(bflo(gw.w)); z1[3] = sigmoidf_(bfhi(gw.w));
;                     const f32x4 q0 = {bflo(pw.x), bfhi(pw.x), bflo(pw.y), bfhi(pw.y)}, q1 = {bflo(pw.z), bfhi(pw.z), bflo(pw.w), bfhi(pw.w)};
;                     z0 = z0 * acc[ai][bj][m][0] + q0; z1 = z1 * acc[ai][bj][m][1] + q1;
;                     u32x4 w; w.x = pk2(z0[0], z0[1]); w.y = pk2(z0[2], z0[3]); w.z = pk2(z1[0], z1[1]); w.w = pk2(z1[2], z1[3]);
;                     *(gu32x4*)(dst + row * DM + col) = w; } }
	v_lshlrev_b32_e32 v214, 16, v180
	v_and_b32_e32 v215, 0xffff0000, v180
	v_lshlrev_b32_e32 v216, 16, v181
	v_and_b32_e32 v217, 0xffff0000, v181
	v_lshlrev_b32_e32 v218, 16, v182
	v_and_b32_e32 v219, 0xffff0000, v182
	v_lshlrev_b32_e32 v220, 16, v183
	v_and_b32_e32 v221, 0xffff0000, v183
	v_mul_f32_e32 v214, 0xbfb8aa3b, v214
	v_mul_f32_e32 v215, 0xbfb8aa3b, v215
	v_mul_f32_e32 v216, 0xbfb8aa3b, v216
	v_mul_f32_e32 v217, 0xbfb8aa3b, v217
	v_mul_f32_e32 v218, 0xbfb8aa3b, v218
	v_mul_f32_e32 v219, 0xbfb8aa3b, v219
	v_mul_f32_e32 v220, 0xbfb8aa3b, v220
	v_mul_f32_e32 v221, 0xbfb8aa3b, v221
	v_exp_f32_e32 v214, v214
	v_exp_f32_e32 v215, v215
	v_exp_f32_e32 v216, v216
	v_exp_f32_e32 v217, v217
	v_exp_f32_e32 v218, v218
	v_exp_f32_e32 v219, v219
	v_exp_f32_e32 v220, v220
	v_exp_f32_e32 v221, v221
	v_add_f32_e32 v214, 1.0, v214
	v_add_f32_e32 v215, 1.0, v215
	v_add_f32_e32 v216, 1.0, v216
	v_add_f32_e32 v217, 1.0, v217
	v_add_f32_e32 v218, 1.0, v218
	v_add_f32_e32 v219, 1.0, v219
	v_add_f32_e32 v220, 1.0, v220
	v_add_f32_e32 v221, 1.0, v221
	v_rcp_f32_e32 v214, v214
	v_rcp_f32_e32 v215, v215
	v_rcp_f32_e32 v216, v216
	v_rcp_f32_e32 v217, v217
	v_rcp_f32_e32 v218, v218
	v_rcp_f32_e32 v219, v219
	v_rcp_f32_e32 v220, v220
	v_rcp_f32_e32 v221, v221
	v_lshlrev_b32_e32 v222, 16, v188
	v_and_b32_e32 v223, 0xffff0000, v188
	v_pk_fma_f32 v[78:79], v[78:79], v[214:215], v[222:223]
	v_lshlrev_b32_e32 v222, 16, v189
	v_and_b32_e32 v223, 0xffff0000, v189
	v_pk_fma_f32 v[80:81], v[80:81], v[216:217], v[222:223]
	v_lshlrev_b32_e32 v222, 16, v190
	v_and_b32_e32 v223, 0xffff0000, v190
	v_pk_fma_f32 v[74:75], v[74:75], v[218:219], v[222:223]
	v_lshlrev_b32_e32 v222, 16, v191
	v_and_b32_e32 v223, 0xffff0000, v191
	v_pk_fma_f32 v[76:77], v[76:77], v[220:221], v[222:223]
	v_cvt_pk_bf16_f32 v180, v78, v79
	v_cvt_pk_bf16_f32 v181, v80, v81
	v_cvt_pk_bf16_f32 v182, v74, v75
	v_cvt_pk_bf16_f32 v183, v76, v77
	v_lshlrev_b32_e32 v214, 16, v184
	v_and_b32_e32 v215, 0xffff0000, v184
	v_lshlrev_b32_e32 v216, 16, v185
	v_and_b32_e32 v217, 0xffff0000, v185
	v_lshlrev_b32_e32 v218, 16, v186
	v_and_b32_e32 v219, 0xffff0000, v186
	v_lshlrev_b32_e32 v220, 16, v187
	v_and_b32_e32 v221, 0xffff0000, v187
	v_mul_f32_e32 v214, 0xbfb8aa3b, v214
	v_mul_f32_e32 v215, 0xbfb8aa3b, v215
	v_mul_f32_e32 v216, 0xbfb8aa3b, v216
	v_mul_f32_e32 v217, 0xbfb8aa3b, v217
	v_mul_f32_e32 v218, 0xbfb8aa3b, v218
	v_mul_f32_e32 v219, 0xbfb8aa3b, v219
	v_mul_f32_e32 v220, 0xbfb8aa3b, v220
	v_mul_f32_e32 v221, 0xbfb8aa3b, v221
	v_exp_f32_e32 v214, v214
	v_exp_f32_e32 v215, v215
	v_exp_f32_e32 v216, v216
	v_exp_f32_e32 v217, v217
	v_exp_f32_e32 v218, v218
	v_exp_f32_e32 v219, v219
	v_exp_f32_e32 v220, v220
	v_exp_f32_e32 v221, v221
	v_add_f32_e32 v214, 1.0, v214
	v_add_f32_e32 v215, 1.0, v215
	v_add_f32_e32 v216, 1.0, v216
	v_add_f32_e32 v217, 1.0, v217
	v_add_f32_e32 v218, 1.0, v218
	v_add_f32_e32 v219, 1.0, v219
	v_add_f32_e32 v220, 1.0, v220
	v_add_f32_e32 v221, 1.0, v221
	v_rcp_f32_e32 v214, v214
	v_rcp_f32_e32 v215, v215
	v_rcp_f32_e32 v216, v216
	v_rcp_f32_e32 v217, v217
	v_rcp_f32_e32 v218, v218
	v_rcp_f32_e32 v219, v219
	v_rcp_f32_e32 v220, v220
	v_rcp_f32_e32 v221, v221
	v_lshlrev_b32_e32 v222, 16, v192
	v_and_b32_e32 v223, 0xffff0000, v192
	v_pk_fma_f32 v[70:71], v[70:71], v[214:215], v[222:223]
	v_lshlrev_b32_e32 v222, 16, v193
	v_and_b32_e32 v223, 0xffff0000, v193
	v_pk_fma_f32 v[72:73], v[72:73], v[216:217], v[222:223]
	v_lshlrev_b32_e32 v222, 16, v194
	v_and_b32_e32 v223, 0xffff0000, v194
	v_pk_fma_f32 v[66:67], v[66:67], v[218:219], v[222:223]
	v_lshlrev_b32_e32 v222, 16, v195
	v_and_b32_e32 v223, 0xffff0000, v195
	v_pk_fma_f32 v[68:69], v[68:69], v[220:221], v[222:223]
	v_cvt_pk_bf16_f32 v184, v70, v71
	v_cvt_pk_bf16_f32 v185, v72, v73
	v_cvt_pk_bf16_f32 v186, v66, v67
	v_cvt_pk_bf16_f32 v187, v68, v69
	global_store_dwordx4 v123, v[180:183], s[16:17]
	global_store_dwordx4 v123, v[184:187], s[16:17] offset:256
	s_add_u32 s16, s16, 0x28000
	s_addc_u32 s17, s17, 0
	global_load_dwordx4 v[180:183], v122, s[0:1]
	global_load_dwordx4 v[184:187], v122, s[0:1] offset:256
	global_load_dwordx4 v[188:191], v123, s[4:5]
	global_load_dwordx4 v[192:195], v123, s[4:5] offset:256
	s_add_u32 s0, s0, 0xc8000
	s_addc_u32 s1, s1, 0
	s_add_u32 s4, s4, 0x28000
	s_addc_u32 s5, s5, 0
	s_waitcnt vmcnt(18)
; __device__ __forceinline__ unsigned pk2(float lo, float hi) { f32x2 v = {lo, hi}; bf16x2_t b = __builtin_convertvector(v, bf16x2_t); return __builtin_bit_cast(unsigned, b); }
; __device__ __forceinline__ float bflo(unsigned w) { return __uint_as_float(w << 16); }
; __device__ __forceinline__ float bfhi(unsigned w) { return __uint_as_float(w & 0xffff0000u); }
; __device__ __forceinline__ float sigmoidf_(float x) { return __builtin_amdgcn_rcpf(1.0f + __builtin_amdgcn_exp2f(-x * LOG2E)); }
;     __device__ __forceinline__ void operator()(const f32x4 (&acc)[2][2][4][2], const Unit& u, int wr, int wc, int fr, int fq, LAS unsigned char* lds, int tid) const {
;     ...
;             for (int m = 0; m < 4; ++m) { const size_t row = (size_t)(row0 + ai * HALF + m * 16);
; #pragma unroll
;                 for (int bj = 0; bj < 2; ++bj) { const int col = col0 + bj * HALF;
;                     gv[m][bj] = *(const gu32x4*)(proj + row * PROJ + 2048 + 1024 * pz + col);
;                     if (pz != 0) pv[m][bj] = *(const gu32x4*)(part + row * DM + col); else pv[m][bj] = (u32x4){0u, 0u, 0u, 0u}; } }
;             asm volatile("" ::: "memory");
; #pragma unroll
;             for (int m = 0; m < 4; ++m) { const size_t row = (size_t)(row0 + ai * HALF + m * 16);
; #pragma unroll
;                 for (int bj = 0; bj < 2; ++bj) { const int col = col0 + bj * HALF; const u32x4 gw = gv[m][bj], pw = pv[m][bj];
;                     f32x4 z0, z1;
;                     z0[0] = sigmoidf_(bflo(gw.x)); z0[1] = sigmoidf_(bfhi(gw.x)); z0[2] = sigmoidf_(bflo(gw.y)); z0[3] = sigmoidf_(bfhi(gw.y));
;                     z1[0] = sigmoidf_(bflo(gw.z)); z1[1] = sigmoidf_(bfhi(gw.z)); z1[2] = sigmoidf_(bflo(gw.w)); z1[3] = sigmoidf_(bfhi(gw.w));
;                     const f32x4 q0 = {bflo(pw.x), bfhi(pw.x), bflo(pw.y), bfhi(pw.y)}, q1 = {bflo(pw.z), bfhi(pw.z), bflo(pw.w), bfhi(pw.w)};
;                     z0 = z0 * acc[ai][bj][m][0] + q0; z1 = z1 * acc[ai][bj][m][1] + q1;
;                     u32x4 w; w.x = pk2(z0[0], z0[1]); w.y = pk2(z0[2], z0[3]); w.z = pk2(z1[0], z1[1]); w.w = pk2(z1[2], z1[3]);
;                     *(gu32x4*)(dst + row * DM + col) = w; } }
	v_lshlrev_b32_e32 v214, 16, v132
	v_and_b32_e32 v215, 0xffff0000, v132
	v_lshlrev_b32_e32 v216, 16, v133
	v_and_b32_e32 v217, 0xffff0000, v133
	v_lshlrev_b32_e32 v218, 16, v134
	v_and_b32_e32 v219, 0xffff0000, v134
	v_lshlrev_b32_e32 v220, 16, v135
	v_and_b32_e32 v221, 0xffff0000, v135
	v_mul_f32_e32 v214, 0xbfb8aa3b, v214
	v_mul_f32_e32 v215, 0xbfb8aa3b, v215
	v_mul_f32_e32 v216, 0xbfb8aa3b, v216
	v_mul_f32_e32 v217, 0xbfb8aa3b, v217
	v_mul_f32_e32 v218, 0xbfb8aa3b, v218
	v_mul_f32_e32 v219, 0xbfb8aa3b, v219
	v_mul_f32_e32 v220, 0xbfb8aa3b, v220
	v_mul_f32_e32 v221, 0xbfb8aa3b, v221
	v_exp_f32_e32 v214, v214
	v_exp_f32_e32 v215, v215
	v_exp_f32_e32 v216, v216
	v_exp_f32_e32 v217, v217
	v_exp_f32_e32 v218, v218
	v_exp_f32_e32 v219, v219
	v_exp_f32_e32 v220, v220
	v_exp_f32_e32 v221, v221
	v_add_f32_e32 v214, 1.0, v214
	v_add_f32_e32 v215, 1.0, v215
	v_add_f32_e32 v216, 1.0, v216
	v_add_f32_e32 v217, 1.0, v217
	v_add_f32_e32 v218, 1.0, v218
	v_add_f32_e32 v219, 1.0, v219
	v_add_f32_e32 v220, 1.0, v220
	v_add_f32_e32 v221, 1.0, v221
	v_rcp_f32_e32 v214, v214
	v_rcp_f32_e32 v215, v215
	v_rcp_f32_e32 v216, v216
	v_rcp_f32_e32 v217, v217
	v_rcp_f32_e32 v218, v218
	v_rcp_f32_e32 v219, v219
	v_rcp_f32_e32 v220, v220
	v_rcp_f32_e32 v221, v221
	v_lshlrev_b32_e32 v222, 16, v140
	v_and_b32_e32 v223, 0xffff0000, v140
	v_pk_fma_f32 v[62:63], v[62:63], v[214:215], v[222:223]
	v_lshlrev_b32_e32 v222, 16, v141
	v_and_b32_e32 v223, 0xffff0000, v141
	v_pk_fma_f32 v[64:65], v[64:65], v[216:217], v[222:223]
	v_lshlrev_b32_e32 v222, 16, v142
	v_and_b32_e32 v223, 0xffff0000, v142
	v_pk_fma_f32 v[58:59], v[58:59], v[218:219], v[222:223]
	v_lshlrev_b32_e32 v222, 16, v143
	v_and_b32_e32 v223, 0xffff0000, v143
	v_pk_fma_f32 v[60:61], v[60:61], v[220:221], v[222:223]
	v_cvt_pk_bf16_f32 v132, v62, v63
	v_cvt_pk_bf16_f32 v133, v64, v65
	v_cvt_pk_bf16_f32 v134, v58, v59
	v_cvt_pk_bf16_f32 v135, v60, v61
	v_lshlrev_b32_e32 v214, 16, v136
	v_and_b32_e32 v215, 0xffff0000, v136
	v_lshlrev_b32_e32 v216, 16, v137
	v_and_b32_e32 v217, 0xffff0000, v137
	v_lshlrev_b32_e32 v218, 16, v138
	v_and_b32_e32 v219, 0xffff0000, v138
	v_lshlrev_b32_e32 v220, 16, v139
	v_and_b32_e32 v221, 0xffff0000, v139
	v_mul_f32_e32 v214, 0xbfb8aa3b, v214
	v_mul_f32_e32 v215, 0xbfb8aa3b, v215
	v_mul_f32_e32 v216, 0xbfb8aa3b, v216
	v_mul_f32_e32 v217, 0xbfb8aa3b, v217
	v_mul_f32_e32 v218, 0xbfb8aa3b, v218
	v_mul_f32_e32 v219, 0xbfb8aa3b, v219
	v_mul_f32_e32 v220, 0xbfb8aa3b, v220
	v_mul_f32_e32 v221, 0xbfb8aa3b, v221
	v_exp_f32_e32 v214, v214
	v_exp_f32_e32 v215, v215
	v_exp_f32_e32 v216, v216
	v_exp_f32_e32 v217, v217
	v_exp_f32_e32 v218, v218
	v_exp_f32_e32 v219, v219
	v_exp_f32_e32 v220, v220
	v_exp_f32_e32 v221, v221
	v_add_f32_e32 v214, 1.0, v214
	v_add_f32_e32 v215, 1.0, v215
	v_add_f32_e32 v216, 1.0, v216
	v_add_f32_e32 v217, 1.0, v217
	v_add_f32_e32 v218, 1.0, v218
	v_add_f32_e32 v219, 1.0, v219
	v_add_f32_e32 v220, 1.0, v220
	v_add_f32_e32 v221, 1.0, v221
	v_rcp_f32_e32 v214, v214
	v_rcp_f32_e32 v215, v215
	v_rcp_f32_e32 v216, v216
	v_rcp_f32_e32 v217, v217
	v_rcp_f32_e32 v218, v218
	v_rcp_f32_e32 v219, v219
	v_rcp_f32_e32 v220, v220
	v_rcp_f32_e32 v221, v221
	v_lshlrev_b32_e32 v222, 16, v144
	v_and_b32_e32 v223, 0xffff0000, v144
	v_pk_fma_f32 v[54:55], v[54:55], v[214:215], v[222:223]
	v_lshlrev_b32_e32 v222, 16, v145
	v_and_b32_e32 v223, 0xffff0000, v145
	v_pk_fma_f32 v[56:57], v[56:57], v[216:217], v[222:223]
	v_lshlrev_b32_e32 v222, 16, v146
	v_and_b32_e32 v223, 0xffff0000, v146
	v_pk_fma_f32 v[50:51], v[50:51], v[218:219], v[222:223]
	v_lshlrev_b32_e32 v222, 16, v147
	v_and_b32_e32 v223, 0xffff0000, v147
	v_pk_fma_f32 v[52:53], v[52:53], v[220:221], v[222:223]
	v_cvt_pk_bf16_f32 v136, v54, v55
	v_cvt_pk_bf16_f32 v137, v56, v57
	v_cvt_pk_bf16_f32 v138, v50, v51
	v_cvt_pk_bf16_f32 v139, v52, v53
	global_store_dwordx4 v123, v[132:135], s[16:17]
	global_store_dwordx4 v123, v[136:139], s[16:17] offset:256
	s_add_u32 s16, s16, 0x8000
	s_addc_u32 s17, s17, 0
	s_waitcnt vmcnt(14)
	v_lshlrev_b32_e32 v214, 16, v148
	v_and_b32_e32 v215, 0xffff0000, v148
	v_lshlrev_b32_e32 v216, 16, v149
	v_and_b32_e32 v217, 0xffff0000, v149
	v_lshlrev_b32_e32 v218, 16, v150
	v_and_b32_e32 v219, 0xffff0000, v150
	v_lshlrev_b32_e32 v220, 16, v151
	v_and_b32_e32 v221, 0xffff0000, v151
	v_mul_f32_e32 v214, 0xbfb8aa3b, v214
	v_mul_f32_e32 v215, 0xbfb8aa3b, v215
	v_mul_f32_e32 v216, 0xbfb8aa3b, v216
	v_mul_f32_e32 v217, 0xbfb8aa3b, v217
	v_mul_f32_e32 v218, 0xbfb8aa3b, v218
	v_mul_f32_e32 v219, 0xbfb8aa3b, v219
	v_mul_f32_e32 v220, 0xbfb8aa3b, v220
	v_mul_f32_e32 v221, 0xbfb8aa3b, v221
	v_exp_f32_e32 v214, v214
	v_exp_f32_e32 v215, v215
	v_exp_f32_e32 v216, v216
	v_exp_f32_e32 v217, v217
	v_exp_f32_e32 v218, v218
	v_exp_f32_e32 v219, v219
	v_exp_f32_e32 v220, v220
	v_exp_f32_e32 v221, v221
	v_add_f32_e32 v214, 1.0, v214
	v_add_f32_e32 v215, 1.0, v215
	v_add_f32_e32 v216, 1.0, v216
	v_add_f32_e32 v217, 1.0, v217
	v_add_f32_e32 v218, 1.0, v218
	v_add_f32_e32 v219, 1.0, v219
	v_add_f32_e32 v220, 1.0, v220
	v_add_f32_e32 v221, 1.0, v221
	v_rcp_f32_e32 v214, v214
	v_rcp_f32_e32 v215, v215
	v_rcp_f32_e32 v216, v216
	v_rcp_f32_e32 v217, v217
	v_rcp_f32_e32 v218, v218
	v_rcp_f32_e32 v219, v219
	v_rcp_f32_e32 v220, v220
	v_rcp_f32_e32 v221, v221
	v_lshlrev_b32_e32 v222, 16, v156
	v_and_b32_e32 v223, 0xffff0000, v156
	v_pk_fma_f32 v[46:47], v[46:47], v[214:215], v[222:223]
	v_lshlrev_b32_e32 v222, 16, v157
	v_and_b32_e32 v223, 0xffff0000, v157
	v_pk_fma_f32 v[48:49], v[48:49], v[216:217], v[222:223]
	v_lshlrev_b32_e32 v222, 16, v158
	v_and_b32_e32 v223, 0xffff0000, v158
	v_pk_fma_f32 v[42:43], v[42:43], v[218:219], v[222:223]
; __device__ __forceinline__ unsigned pk2(float lo, float hi) { f32x2 v = {lo, hi}; bf16x2_t b = __builtin_convertvector(v, bf16x2_t); return __builtin_bit_cast(unsigned, b); }
; __device__ __forceinline__ float bflo(unsigned w) { return __uint_as_float(w << 16); }
; __device__ __forceinline__ float bfhi(unsigned w) { return __uint_as_float(w & 0xffff0000u); }
; __device__ __forceinline__ float sigmoidf_(float x) { return __builtin_amdgcn_rcpf(1.0f + __builtin_amdgcn_exp2f(-x * LOG2E)); }
;     __device__ __forceinline__ void operator()(const f32x4 (&acc)[2][2][4][2], const Unit& u, int wr, int wc, int fr, int fq, LAS unsigned char* lds, int tid) const {
;     ...
;             for (int m = 0; m < 4; ++m) { const size_t row = (size_t)(row0 + ai * HALF + m * 16);
; #pragma unroll
;                 for (int bj = 0; bj < 2; ++bj) { const int col = col0 + bj * HALF;
;                     gv[m][bj] = *(const gu32x4*)(proj + row * PROJ + 2048 + 1024 * pz + col);
;                     if (pz != 0) pv[m][bj] = *(const gu32x4*)(part + row * DM + col); else pv[m][bj] = (u32x4){0u, 0u, 0u, 0u}; } }
;             asm volatile("" ::: "memory");
; #pragma unroll
;             for (int m = 0; m < 4; ++m) { const size_t row = (size_t)(row0 + ai * HALF + m * 16);
; #pragma unroll
;                 for (int bj = 0; bj < 2; ++bj) { const int col = col0 + bj * HALF; const u32x4 gw = gv[m][bj], pw = pv[m][bj];
;                     f32x4 z0, z1;
;                     z0[0] = sigmoidf_(bflo(gw.x)); z0[1] = sigmoidf_(bfhi(gw.x)); z0[2] = sigmoidf_(bflo(gw.y)); z0[3] = sigmoidf_(bfhi(gw.y));
;                     z1[0] = sigmoidf_(bflo(gw.z)); z1[1] = sigmoidf_(bfhi(gw.z)); z1[2] = sigmoidf_(bflo(gw.w)); z1[3] = sigmoidf_(bfhi(gw.w));
;                     const f32x4 q0 = {bflo(pw.x), bfhi(pw.x), bflo(pw.y), bfhi(pw.y)}, q1 = {bflo(pw.z), bfhi(pw.z), bflo(pw.w), bfhi(pw.w)};
;                     z0 = z0 * acc[ai][bj][m][0] + q0; z1 = z1 * acc[ai][bj][m][1] + q1;
;                     u32x4 w; w.x = pk2(z0[0], z0[1]); w.y = pk2(z0[2], z0[3]); w.z = pk2(z1[0], z1[1]); w.w = pk2(z1[2], z1[3]);
;                     *(gu32x4*)(dst + row * DM + col) = w; } }
	v_lshlrev_b32_e32 v222, 16, v159
	v_and_b32_e32 v223, 0xffff0000, v159
	v_pk_fma_f32 v[44:45], v[44:45], v[220:221], v[222:223]
	v_cvt_pk_bf16_f32 v148, v46, v47
	v_cvt_pk_bf16_f32 v149, v48, v49
	v_cvt_pk_bf16_f32 v150, v42, v43
	v_cvt_pk_bf16_f32 v151, v44, v45
	v_lshlrev_b32_e32 v214, 16, v152
	v_and_b32_e32 v215, 0xffff0000, v152
	v_lshlrev_b32_e32 v216, 16, v153
	v_and_b32_e32 v217, 0xffff0000, v153
	v_lshlrev_b32_e32 v218, 16, v154
	v_and_b32_e32 v219, 0xffff0000, v154
	v_lshlrev_b32_e32 v220, 16, v155
	v_and_b32_e32 v221, 0xffff0000, v155
	v_mul_f32_e32 v214, 0xbfb8aa3b, v214
	v_mul_f32_e32 v215, 0xbfb8aa3b, v215
	v_mul_f32_e32 v216, 0xbfb8aa3b, v216
	v_mul_f32_e32 v217, 0xbfb8aa3b, v217
	v_mul_f32_e32 v218, 0xbfb8aa3b, v218
	v_mul_f32_e32 v219, 0xbfb8aa3b, v219
	v_mul_f32_e32 v220, 0xbfb8aa3b, v220
	v_mul_f32_e32 v221, 0xbfb8aa3b, v221
	v_exp_f32_e32 v214, v214
	v_exp_f32_e32 v215, v215
	v_exp_f32_e32 v216, v216
	v_exp_f32_e32 v217, v217
	v_exp_f32_e32 v218, v218
	v_exp_f32_e32 v219, v219
	v_exp_f32_e32 v220, v220
	v_exp_f32_e32 v221, v221
	v_add_f32_e32 v214, 1.0, v214
	v_add_f32_e32 v215, 1.0, v215
	v_add_f32_e32 v216, 1.0, v216
	v_add_f32_e32 v217, 1.0, v217
	v_add_f32_e32 v218, 1.0, v218
	v_add_f32_e32 v219, 1.0, v219
	v_add_f32_e32 v220, 1.0, v220
	v_add_f32_e32 v221, 1.0, v221
	v_rcp_f32_e32 v214, v214
	v_rcp_f32_e32 v215, v215
	v_rcp_f32_e32 v216, v216
	v_rcp_f32_e32 v217, v217
	v_rcp_f32_e32 v218, v218
	v_rcp_f32_e32 v219, v219
	v_rcp_f32_e32 v220, v220
	v_rcp_f32_e32 v221, v221
	v_lshlrev_b32_e32 v222, 16, v160
	v_and_b32_e32 v223, 0xffff0000, v160
	v_pk_fma_f32 v[38:39], v[38:39], v[214:215], v[222:223]
	v_lshlrev_b32_e32 v222, 16, v161
	v_and_b32_e32 v223, 0xffff0000, v161
	v_pk_fma_f32 v[40:41], v[40:41], v[216:217], v[222:223]
	v_lshlrev_b32_e32 v222, 16, v162
	v_and_b32_e32 v223, 0xffff0000, v162
	v_pk_fma_f32 v[34:35], v[34:35], v[218:219], v[222:223]
	v_lshlrev_b32_e32 v222, 16, v163
	v_and_b32_e32 v223, 0xffff0000, v163
	v_pk_fma_f32 v[36:37], v[36:37], v[220:221], v[222:223]
	v_cvt_pk_bf16_f32 v152, v38, v39
	v_cvt_pk_bf16_f32 v153, v40, v41
	v_cvt_pk_bf16_f32 v154, v34, v35
	v_cvt_pk_bf16_f32 v155, v36, v37
	global_store_dwordx4 v123, v[148:151], s[16:17]
	global_store_dwordx4 v123, v[152:155], s[16:17] offset:256
	s_add_u32 s16, s16, 0x8000
	s_addc_u32 s17, s17, 0
	s_waitcnt vmcnt(10)
	v_lshlrev_b32_e32 v214, 16, v164
	v_and_b32_e32 v215, 0xffff0000, v164
	v_lshlrev_b32_e32 v216, 16, v165
	v_and_b32_e32 v217, 0xffff0000, v165
	v_lshlrev_b32_e32 v218, 16, v166
	v_and_b32_e32 v219, 0xffff0000, v166
	v_lshlrev_b32_e32 v220, 16, v167
	v_and_b32_e32 v221, 0xffff0000, v167
	v_mul_f32_e32 v214, 0xbfb8aa3b, v214
	v_mul_f32_e32 v215, 0xbfb8aa3b, v215
	v_mul_f32_e32 v216, 0xbfb8aa3b, v216
	v_mul_f32_e32 v217, 0xbfb8aa3b, v217
	v_mul_f32_e32 v218, 0xbfb8aa3b, v218
	v_mul_f32_e32 v219, 0xbfb8aa3b, v219
	v_mul_f32_e32 v220, 0xbfb8aa3b, v220
	v_mul_f32_e32 v221, 0xbfb8aa3b, v221
	v_exp_f32_e32 v214, v214
	v_exp_f32_e32 v215, v215
	v_exp_f32_e32 v216, v216
	v_exp_f32_e32 v217, v217
	v_exp_f32_e32 v218, v218
	v_exp_f32_e32 v219, v219
	v_exp_f32_e32 v220, v220
	v_exp_f32_e32 v221, v221
	v_add_f32_e32 v214, 1.0, v214
	v_add_f32_e32 v215, 1.0, v215
	v_add_f32_e32 v216, 1.0, v216
	v_add_f32_e32 v217, 1.0, v217
	v_add_f32_e32 v218, 1.0, v218
	v_add_f32_e32 v219, 1.0, v219
	v_add_f32_e32 v220, 1.0, v220
	v_add_f32_e32 v221, 1.0, v221
	v_rcp_f32_e32 v214, v214
	v_rcp_f32_e32 v215, v215
	v_rcp_f32_e32 v216, v216
	v_rcp_f32_e32 v217, v217
	v_rcp_f32_e32 v218, v218
	v_rcp_f32_e32 v219, v219
	v_rcp_f32_e32 v220, v220
	v_rcp_f32_e32 v221, v221
	v_lshlrev_b32_e32 v222, 16, v172
	v_and_b32_e32 v223, 0xffff0000, v172
	v_pk_fma_f32 v[30:31], v[30:31], v[214:215], v[222:223]
	v_lshlrev_b32_e32 v222, 16, v173
	v_and_b32_e32 v223, 0xffff0000, v173
	v_pk_fma_f32 v[32:33], v[32:33], v[216:217], v[222:223]
	v_lshlrev_b32_e32 v222, 16, v174
	v_and_b32_e32 v223, 0xffff0000, v174
	v_pk_fma_f32 v[26:27], v[26:27], v[218:219], v[222:223]
	v_lshlrev_b32_e32 v222, 16, v175
	v_and_b32_e32 v223, 0xffff0000, v175
	v_pk_fma_f32 v[28:29], v[28:29], v[220:221], v[222:223]
	v_cvt_pk_bf16_f32 v164, v30, v31
	v_cvt_pk_bf16_f32 v165, v32, v33
	v_cvt_pk_bf16_f32 v166, v26, v27
	v_cvt_pk_bf16_f32 v167, v28, v29
	v_lshlrev_b32_e32 v214, 16, v168
	v_and_b32_e32 v215, 0xffff0000, v168
	v_lshlrev_b32_e32 v216, 16, v169
	v_and_b32_e32 v217, 0xffff0000, v169
	v_lshlrev_b32_e32 v218, 16, v170
	v_and_b32_e32 v219, 0xffff0000, v170
	v_lshlrev_b32_e32 v220, 16, v171
	v_and_b32_e32 v221, 0xffff0000, v171
	v_mul_f32_e32 v214, 0xbfb8aa3b, v214
	v_mul_f32_e32 v215, 0xbfb8aa3b, v215
	v_mul_f32_e32 v216, 0xbfb8aa3b, v216
	v_mul_f32_e32 v217, 0xbfb8aa3b, v217
	v_mul_f32_e32 v218, 0xbfb8aa3b, v218
	v_mul_f32_e32 v219, 0xbfb8aa3b, v219
	v_mul_f32_e32 v220, 0xbfb8aa3b, v220
	v_mul_f32_e32 v221, 0xbfb8aa3b, v221
	v_exp_f32_e32 v214, v214
	v_exp_f32_e32 v215, v215
	v_exp_f32_e32 v216, v216
	v_exp_f32_e32 v217, v217
	v_exp_f32_e32 v218, v218
	v_exp_f32_e32 v219, v219
	v_exp_f32_e32 v220, v220
	v_exp_f32_e32 v221, v221
	v_add_f32_e32 v214, 1.0, v214
	v_add_f32_e32 v215, 1.0, v215
	v_add_f32_e32 v216, 1.0, v216
	v_add_f32_e32 v217, 1.0, v217
	v_add_f32_e32 v218, 1.0, v218
	v_add_f32_e32 v219, 1.0, v219
	v_add_f32_e32 v220, 1.0, v220
	v_add_f32_e32 v221, 1.0, v221
	v_rcp_f32_e32 v214, v214
	v_rcp_f32_e32 v215, v215
	v_rcp_f32_e32 v216, v216
	v_rcp_f32_e32 v217, v217
	v_rcp_f32_e32 v218, v218
	v_rcp_f32_e32 v219, v219
	v_rcp_f32_e32 v220, v220
	v_rcp_f32_e32 v221, v221
	v_lshlrev_b32_e32 v222, 16, v176
	v_and_b32_e32 v223, 0xffff0000, v176
	v_pk_fma_f32 v[22:23], v[22:23], v[214:215], v[222:223]
	v_lshlrev_b32_e32 v222, 16, v177
	v_and_b32_e32 v223, 0xffff0000, v177
	v_pk_fma_f32 v[24:25], v[24:25], v[216:217], v[222:223]
	v_lshlrev_b32_e32 v222, 16, v178
	v_and_b32_e32 v223, 0xffff0000, v178
	v_pk_fma_f32 v[18:19], v[18:19], v[218:219], v[222:223]
	v_lshlrev_b32_e32 v222, 16, v179
	v_and_b32_e32 v223, 0xffff0000, v179
	v_pk_fma_f32 v[20:21], v[20:21], v[220:221], v[222:223]
	v_cvt_pk_bf16_f32 v168, v22, v23
	v_cvt_pk_bf16_f32 v169, v24, v25
	v_cvt_pk_bf16_f32 v170, v18, v19
	v_cvt_pk_bf16_f32 v171, v20, v21
	global_store_dwordx4 v123, v[164:167], s[16:17]
	global_store_dwordx4 v123, v[168:171], s[16:17] offset:256
	s_add_u32 s16, s16, 0x8000
	s_addc_u32 s17, s17, 0
	s_waitcnt vmcnt(6)
; __device__ __forceinline__ unsigned pk2(float lo, float hi) { f32x2 v = {lo, hi}; bf16x2_t b = __builtin_convertvector(v, bf16x2_t); return __builtin_bit_cast(unsigned, b); }
; __device__ __forceinline__ float bflo(unsigned w) { return __uint_as_float(w << 16); }
; __device__ __forceinline__ float bfhi(unsigned w) { return __uint_as_float(w & 0xffff0000u); }
; __device__ __forceinline__ float sigmoidf_(float x) { return __builtin_amdgcn_rcpf(1.0f + __builtin_amdgcn_exp2f(-x * LOG2E)); }
;     __device__ __forceinline__ void operator()(const f32x4 (&acc)[2][2][4][2], const Unit& u, int wr, int wc, int fr, int fq, LAS unsigned char* lds, int tid) const {
;     ...
;             for (int m = 0; m < 4; ++m) { const size_t row = (size_t)(row0 + ai * HALF + m * 16);
; #pragma unroll
;                 for (int bj = 0; bj < 2; ++bj) { const int col = col0 + bj * HALF;
;                     gv[m][bj] = *(const gu32x4*)(proj + row * PROJ + 2048 + 1024 * pz + col);
;                     if (pz != 0) pv[m][bj] = *(const gu32x4*)(part + row * DM + col); else pv[m][bj] = (u32x4){0u, 0u, 0u, 0u}; } }
;             asm volatile("" ::: "memory");
; #pragma unroll
;             for (int m = 0; m < 4; ++m) { const size_t row = (size_t)(row0 + ai * HALF + m * 16);
; #pragma unroll
;                 for (int bj = 0; bj < 2; ++bj) { const int col = col0 + bj * HALF; const u32x4 gw = gv[m][bj], pw = pv[m][bj];
;                     f32x4 z0, z1;
;                     z0[0] = sigmoidf_(bflo(gw.x)); z0[1] = sigmoidf_(bfhi(gw.x)); z0[2] = sigmoidf_(bflo(gw.y)); z0[3] = sigmoidf_(bfhi(gw.y));
;                     z1[0] = sigmoidf_(bflo(gw.z)); z1[1] = sigmoidf_(bfhi(gw.z)); z1[2] = sigmoidf_(bflo(gw.w)); z1[3] = sigmoidf_(bfhi(gw.w));
;                     const f32x4 q0 = {bflo(pw.x), bfhi(pw.x), bflo(pw.y), bfhi(pw.y)}, q1 = {bflo(pw.z), bfhi(pw.z), bflo(pw.w), bfhi(pw.w)};
;                     z0 = z0 * acc[ai][bj][m][0] + q0; z1 = z1 * acc[ai][bj][m][1] + q1;
;                     u32x4 w; w.x = pk2(z0[0], z0[1]); w.y = pk2(z0[2], z0[3]); w.z = pk2(z1[0], z1[1]); w.w = pk2(z1[2], z1[3]);
;                     *(gu32x4*)(dst + row * DM + col) = w; } }
	v_lshlrev_b32_e32 v214, 16, v180
	v_and_b32_e32 v215, 0xffff0000, v180
	v_lshlrev_b32_e32 v216, 16, v181
	v_and_b32_e32 v217, 0xffff0000, v181
	v_lshlrev_b32_e32 v218, 16, v182
	v_and_b32_e32 v219, 0xffff0000, v182
	v_lshlrev_b32_e32 v220, 16, v183
	v_and_b32_e32 v221, 0xffff0000, v183
	v_mul_f32_e32 v214, 0xbfb8aa3b, v214
	v_mul_f32_e32 v215, 0xbfb8aa3b, v215
	v_mul_f32_e32 v216, 0xbfb8aa3b, v216
	v_mul_f32_e32 v217, 0xbfb8aa3b, v217
	v_mul_f32_e32 v218, 0xbfb8aa3b, v218
	v_mul_f32_e32 v219, 0xbfb8aa3b, v219
	v_mul_f32_e32 v220, 0xbfb8aa3b, v220
	v_mul_f32_e32 v221, 0xbfb8aa3b, v221
	v_exp_f32_e32 v214, v214
	v_exp_f32_e32 v215, v215
	v_exp_f32_e32 v216, v216
	v_exp_f32_e32 v217, v217
	v_exp_f32_e32 v218, v218
	v_exp_f32_e32 v219, v219
	v_exp_f32_e32 v220, v220
	v_exp_f32_e32 v221, v221
	v_add_f32_e32 v214, 1.0, v214
	v_add_f32_e32 v215, 1.0, v215
	v_add_f32_e32 v216, 1.0, v216
	v_add_f32_e32 v217, 1.0, v217
	v_add_f32_e32 v218, 1.0, v218
	v_add_f32_e32 v219, 1.0, v219
	v_add_f32_e32 v220, 1.0, v220
	v_add_f32_e32 v221, 1.0, v221
	v_rcp_f32_e32 v214, v214
	v_rcp_f32_e32 v215, v215
	v_rcp_f32_e32 v216, v216
	v_rcp_f32_e32 v217, v217
	v_rcp_f32_e32 v218, v218
	v_rcp_f32_e32 v219, v219
	v_rcp_f32_e32 v220, v220
	v_rcp_f32_e32 v221, v221
	v_lshlrev_b32_e32 v222, 16, v188
	v_and_b32_e32 v223, 0xffff0000, v188
	v_pk_fma_f32 v[14:15], v[14:15], v[214:215], v[222:223]
	v_lshlrev_b32_e32 v222, 16, v189
	v_and_b32_e32 v223, 0xffff0000, v189
	v_pk_fma_f32 v[16:17], v[16:17], v[216:217], v[222:223]
	v_lshlrev_b32_e32 v222, 16, v190
	v_and_b32_e32 v223, 0xffff0000, v190
	v_pk_fma_f32 v[10:11], v[10:11], v[218:219], v[222:223]
	v_lshlrev_b32_e32 v222, 16, v191
	v_and_b32_e32 v223, 0xffff0000, v191
	v_pk_fma_f32 v[12:13], v[12:13], v[220:221], v[222:223]
	v_cvt_pk_bf16_f32 v180, v14, v15
	v_cvt_pk_bf16_f32 v181, v16, v17
	v_cvt_pk_bf16_f32 v182, v10, v11
	v_cvt_pk_bf16_f32 v183, v12, v13
	v_lshlrev_b32_e32 v214, 16, v184
	v_and_b32_e32 v215, 0xffff0000, v184
	v_lshlrev_b32_e32 v216, 16, v185
	v_and_b32_e32 v217, 0xffff0000, v185
	v_lshlrev_b32_e32 v218, 16, v186
	v_and_b32_e32 v219, 0xffff0000, v186
	v_lshlrev_b32_e32 v220, 16, v187
	v_and_b32_e32 v221, 0xffff0000, v187
	v_mul_f32_e32 v214, 0xbfb8aa3b, v214
	v_mul_f32_e32 v215, 0xbfb8aa3b, v215
	v_mul_f32_e32 v216, 0xbfb8aa3b, v216
	v_mul_f32_e32 v217, 0xbfb8aa3b, v217
	v_mul_f32_e32 v218, 0xbfb8aa3b, v218
	v_mul_f32_e32 v219, 0xbfb8aa3b, v219
	v_mul_f32_e32 v220, 0xbfb8aa3b, v220
	v_mul_f32_e32 v221, 0xbfb8aa3b, v221
	v_exp_f32_e32 v214, v214
	v_exp_f32_e32 v215, v215
	v_exp_f32_e32 v216, v216
	v_exp_f32_e32 v217, v217
	v_exp_f32_e32 v218, v218
	v_exp_f32_e32 v219, v219
	v_exp_f32_e32 v220, v220
	v_exp_f32_e32 v221, v221
	v_add_f32_e32 v214, 1.0, v214
	v_add_f32_e32 v215, 1.0, v215
	v_add_f32_e32 v216, 1.0, v216
	v_add_f32_e32 v217, 1.0, v217
	v_add_f32_e32 v218, 1.0, v218
	v_add_f32_e32 v219, 1.0, v219
	v_add_f32_e32 v220, 1.0, v220
	v_add_f32_e32 v221, 1.0, v221
	v_rcp_f32_e32 v214, v214
	v_rcp_f32_e32 v215, v215
	v_rcp_f32_e32 v216, v216
	v_rcp_f32_e32 v217, v217
	v_rcp_f32_e32 v218, v218
	v_rcp_f32_e32 v219, v219
	v_rcp_f32_e32 v220, v220
	v_rcp_f32_e32 v221, v221
	v_lshlrev_b32_e32 v222, 16, v192
	v_and_b32_e32 v223, 0xffff0000, v192
	v_pk_fma_f32 v[6:7], v[6:7], v[214:215], v[222:223]
	v_lshlrev_b32_e32 v222, 16, v193
	v_and_b32_e32 v223, 0xffff0000, v193
	v_pk_fma_f32 v[8:9], v[8:9], v[216:217], v[222:223]
	v_lshlrev_b32_e32 v222, 16, v194
	v_and_b32_e32 v223, 0xffff0000, v194
	v_pk_fma_f32 v[2:3], v[2:3], v[218:219], v[222:223]
	v_lshlrev_b32_e32 v222, 16, v195
	v_and_b32_e32 v223, 0xffff0000, v195
	v_pk_fma_f32 v[4:5], v[4:5], v[220:221], v[222:223]
	v_cvt_pk_bf16_f32 v184, v6, v7
	v_cvt_pk_bf16_f32 v185, v8, v9
	v_cvt_pk_bf16_f32 v186, v2, v3
	v_cvt_pk_bf16_f32 v187, v4, v5
	global_store_dwordx4 v123, v[180:183], s[16:17]
	global_store_dwordx4 v123, v[184:187], s[16:17] offset:256
	s_add_u32 s16, s16, 0x28000
	s_addc_u32 s17, s17, 0
	s_branch .Lgate_done
.Lgate_pz0:
	global_load_dwordx4 v[132:135], v122, s[0:1]
	global_load_dwordx4 v[136:139], v122, s[0:1] offset:256
	s_add_u32 s0, s0, 0x28000
	s_addc_u32 s1, s1, 0
	global_load_dwordx4 v[148:151], v122, s[0:1]
	global_load_dwordx4 v[152:155], v122, s[0:1] offset:256
	s_add_u32 s0, s0, 0x28000
	s_addc_u32 s1, s1, 0
	global_load_dwordx4 v[164:167], v122, s[0:1]
	global_load_dwordx4 v[168:171], v122, s[0:1] offset:256
	s_add_u32 s0, s0, 0x28000
	s_addc_u32 s1, s1, 0
	global_load_dwordx4 v[180:183], v122, s[0:1]
	global_load_dwordx4 v[184:187], v122, s[0:1] offset:256
	s_add_u32 s0, s0, 0xc8000
	s_addc_u32 s1, s1, 0
	s_waitcnt vmcnt(6)
; __device__ __forceinline__ unsigned pk2(float lo, float hi) { f32x2 v = {lo, hi}; bf16x2_t b = __builtin_convertvector(v, bf16x2_t); return __builtin_bit_cast(unsigned, b); }
; __device__ __forceinline__ float bflo(unsigned w) { return __uint_as_float(w << 16); }
; __device__ __forceinline__ float bfhi(unsigned w) { return __uint_as_float(w & 0xffff0000u); }
; __device__ __forceinline__ float sigmoidf_(float x) { return __builtin_amdgcn_rcpf(1.0f + __builtin_amdgcn_exp2f(-x * LOG2E)); }
;     __device__ __forceinline__ void operator()(const f32x4 (&acc)[2][2][4][2], const Unit& u, int wr, int wc, int fr, int fq, LAS unsigned char* lds, int tid) const {
;     ...
;             for (int m = 0; m < 4; ++m) { const size_t row = (size_t)(row0 + ai * HALF + m * 16);
; #pragma unroll
;                 for (int bj = 0; bj < 2; ++bj) { const int col = col0 + bj * HALF; const u32x4 gw = gv[m][bj], pw = pv[m][bj];
;                     f32x4 z0, z1;
;                     z0[0] = sigmoidf_(bflo(gw.x)); z0[1] = sigmoidf_(bfhi(gw.x)); z0[2] = sigmoidf_(bflo(gw.y)); z0[3] = sigmoidf_(bfhi(gw.y));
;                     z1[0] = sigmoidf_(bflo(gw.z)); z1[1] = sigmoidf_(bfhi(gw.z)); z1[2] = sigmoidf_(bflo(gw.w)); z1[3] = sigmoidf_(bfhi(gw.w));
;                     const f32x4 q0 = {bflo(pw.x), bfhi(pw.x), bflo(pw.y), bfhi(pw.y)}, q1 = {bflo(pw.z), bfhi(pw.z), bflo(pw.w), bfhi(pw.w)};
;                     z0 = z0 * acc[ai][bj][m][0] + q0; z1 = z1 * acc[ai][bj][m][1] + q1;
;                     u32x4 w; w.x = pk2(z0[0], z0[1]); w.y = pk2(z0[2], z0[3]); w.z = pk2(z1[0], z1[1]); w.w = pk2(z1[2], z1[3]);
;                     *(gu32x4*)(dst + row * DM + col) = w; } }
	v_lshlrev_b32_e32 v214, 16, v132
	v_and_b32_e32 v215, 0xffff0000, v132
	v_lshlrev_b32_e32 v216, 16, v133
	v_and_b32_e32 v217, 0xffff0000, v133
	v_lshlrev_b32_e32 v218, 16, v134
	v_and_b32_e32 v219, 0xffff0000, v134
	v_lshlrev_b32_e32 v220, 16, v135
	v_and_b32_e32 v221, 0xffff0000, v135
	v_mul_f32_e32 v214, 0xbfb8aa3b, v214
	v_mul_f32_e32 v215, 0xbfb8aa3b, v215
	v_mul_f32_e32 v216, 0xbfb8aa3b, v216
	v_mul_f32_e32 v217, 0xbfb8aa3b, v217
	v_mul_f32_e32 v218, 0xbfb8aa3b, v218
	v_mul_f32_e32 v219, 0xbfb8aa3b, v219
	v_mul_f32_e32 v220, 0xbfb8aa3b, v220
	v_mul_f32_e32 v221, 0xbfb8aa3b, v221
	v_exp_f32_e32 v214, v214
	v_exp_f32_e32 v215, v215
	v_exp_f32_e32 v216, v216
	v_exp_f32_e32 v217, v217
	v_exp_f32_e32 v218, v218
	v_exp_f32_e32 v219, v219
	v_exp_f32_e32 v220, v220
	v_exp_f32_e32 v221, v221
	v_add_f32_e32 v214, 1.0, v214
	v_add_f32_e32 v215, 1.0, v215
	v_add_f32_e32 v216, 1.0, v216
	v_add_f32_e32 v217, 1.0, v217
	v_add_f32_e32 v218, 1.0, v218
	v_add_f32_e32 v219, 1.0, v219
	v_add_f32_e32 v220, 1.0, v220
	v_add_f32_e32 v221, 1.0, v221
	v_rcp_f32_e32 v214, v214
	v_rcp_f32_e32 v215, v215
	v_rcp_f32_e32 v216, v216
	v_rcp_f32_e32 v217, v217
	v_rcp_f32_e32 v218, v218
	v_rcp_f32_e32 v219, v219
	v_rcp_f32_e32 v220, v220
	v_rcp_f32_e32 v221, v221
	s_nop 0
	v_fma_f32 v128, v128, v214, 0
	v_fma_f32 v129, v129, v215, 0
	v_fma_f32 v130, v130, v216, 0
	v_fma_f32 v131, v131, v217, 0
	v_fma_f32 v124, v124, v218, 0
	v_fma_f32 v125, v125, v219, 0
	v_fma_f32 v126, v126, v220, 0
	v_fma_f32 v127, v127, v221, 0
	v_cvt_pk_bf16_f32 v132, v128, v129
	v_cvt_pk_bf16_f32 v133, v130, v131
	v_cvt_pk_bf16_f32 v134, v124, v125
	v_cvt_pk_bf16_f32 v135, v126, v127
	v_lshlrev_b32_e32 v214, 16, v136
	v_and_b32_e32 v215, 0xffff0000, v136
	v_lshlrev_b32_e32 v216, 16, v137
	v_and_b32_e32 v217, 0xffff0000, v137
	v_lshlrev_b32_e32 v218, 16, v138
	v_and_b32_e32 v219, 0xffff0000, v138
	v_lshlrev_b32_e32 v220, 16, v139
	v_and_b32_e32 v221, 0xffff0000, v139
	v_mul_f32_e32 v214, 0xbfb8aa3b, v214
	v_mul_f32_e32 v215, 0xbfb8aa3b, v215
	v_mul_f32_e32 v216, 0xbfb8aa3b, v216
	v_mul_f32_e32 v217, 0xbfb8aa3b, v217
	v_mul_f32_e32 v218, 0xbfb8aa3b, v218
	v_mul_f32_e32 v219, 0xbfb8aa3b, v219
	v_mul_f32_e32 v220, 0xbfb8aa3b, v220
	v_mul_f32_e32 v221, 0xbfb8aa3b, v221
	v_exp_f32_e32 v214, v214
	v_exp_f32_e32 v215, v215
	v_exp_f32_e32 v216, v216
	v_exp_f32_e32 v217, v217
	v_exp_f32_e32 v218, v218
	v_exp_f32_e32 v219, v219
	v_exp_f32_e32 v220, v220
	v_exp_f32_e32 v221, v221
	v_add_f32_e32 v214, 1.0, v214
	v_add_f32_e32 v215, 1.0, v215
	v_add_f32_e32 v216, 1.0, v216
	v_add_f32_e32 v217, 1.0, v217
	v_add_f32_e32 v218, 1.0, v218
	v_add_f32_e32 v219, 1.0, v219
	v_add_f32_e32 v220, 1.0, v220
	v_add_f32_e32 v221, 1.0, v221
	v_rcp_f32_e32 v214, v214
	v_rcp_f32_e32 v215, v215
	v_rcp_f32_e32 v216, v216
	v_rcp_f32_e32 v217, v217
	v_rcp_f32_e32 v218, v218
	v_rcp_f32_e32 v219, v219
	v_rcp_f32_e32 v220, v220
	v_rcp_f32_e32 v221, v221
	s_nop 0
	v_fma_f32 v118, v118, v214, 0
	v_fma_f32 v119, v119, v215, 0
	v_fma_f32 v120, v120, v216, 0
	v_fma_f32 v121, v121, v217, 0
	v_fma_f32 v114, v114, v218, 0
	v_fma_f32 v115, v115, v219, 0
	v_fma_f32 v116, v116, v220, 0
	v_fma_f32 v117, v117, v221, 0
	v_cvt_pk_bf16_f32 v136, v118, v119
	v_cvt_pk_bf16_f32 v137, v120, v121
	v_cvt_pk_bf16_f32 v138, v114, v115
	v_cvt_pk_bf16_f32 v139, v116, v117
	global_store_dwordx4 v123, v[132:135], s[16:17]
	global_store_dwordx4 v123, v[136:139], s[16:17] offset:256
	s_add_u32 s16, s16, 0x8000
	s_addc_u32 s17, s17, 0
	global_load_dwordx4 v[132:135], v122, s[0:1]
	global_load_dwordx4 v[136:139], v122, s[0:1] offset:256
	s_add_u32 s0, s0, 0x28000
	s_addc_u32 s1, s1, 0
	s_waitcnt vmcnt(8)
	v_lshlrev_b32_e32 v214, 16, v148
	v_and_b32_e32 v215, 0xffff0000, v148
	v_lshlrev_b32_e32 v216, 16, v149
	v_and_b32_e32 v217, 0xffff0000, v149
	v_lshlrev_b32_e32 v218, 16, v150
	v_and_b32_e32 v219, 0xffff0000, v150
	v_lshlrev_b32_e32 v220, 16, v151
	v_and_b32_e32 v221, 0xffff0000, v151
	v_mul_f32_e32 v214, 0xbfb8aa3b, v214
	v_mul_f32_e32 v215, 0xbfb8aa3b, v215
	v_mul_f32_e32 v216, 0xbfb8aa3b, v216
	v_mul_f32_e32 v217, 0xbfb8aa3b, v217
	v_mul_f32_e32 v218, 0xbfb8aa3b, v218
	v_mul_f32_e32 v219, 0xbfb8aa3b, v219
	v_mul_f32_e32 v220, 0xbfb8aa3b, v220
	v_mul_f32_e32 v221, 0xbfb8aa3b, v221
	v_exp_f32_e32 v214, v214
	v_exp_f32_e32 v215, v215
	v_exp_f32_e32 v216, v216
	v_exp_f32_e32 v217, v217
	v_exp_f32_e32 v218, v218
	v_exp_f32_e32 v219, v219
	v_exp_f32_e32 v220, v220
	v_exp_f32_e32 v221, v221
	v_add_f32_e32 v214, 1.0, v214
	v_add_f32_e32 v215, 1.0, v215
	v_add_f32_e32 v216, 1.0, v216
	v_add_f32_e32 v217, 1.0, v217
	v_add_f32_e32 v218, 1.0, v218
	v_add_f32_e32 v219, 1.0, v219
	v_add_f32_e32 v220, 1.0, v220
	v_add_f32_e32 v221, 1.0, v221
	v_rcp_f32_e32 v214, v214
	v_rcp_f32_e32 v215, v215
	v_rcp_f32_e32 v216, v216
	v_rcp_f32_e32 v217, v217
	v_rcp_f32_e32 v218, v218
	v_rcp_f32_e32 v219, v219
	v_rcp_f32_e32 v220, v220
	v_rcp_f32_e32 v221, v221
	s_nop 0
	v_fma_f32 v110, v110, v214, 0
	v_fma_f32 v111, v111, v215, 0
	v_fma_f32 v112, v112, v216, 0
	v_fma_f32 v113, v113, v217, 0
	v_fma_f32 v106, v106, v218, 0
	v_fma_f32 v107, v107, v219, 0
	v_fma_f32 v108, v108, v220, 0
	v_fma_f32 v109, v109, v221, 0
	v_cvt_pk_bf16_f32 v148, v110, v111
	v_cvt_pk_bf16_f32 v149, v112, v113
	v_cvt_pk_bf16_f32 v150, v106, v107
	v_cvt_pk_bf16_f32 v151, v108, v109
	v_lshlrev_b32_e32 v214, 16, v152
	v_and_b32_e32 v215, 0xffff0000, v152
	v_lshlrev_b32_e32 v216, 16, v153
	v_and_b32_e32 v217, 0xffff0000, v153
	v_lshlrev_b32_e32 v218, 16, v154
	v_and_b32_e32 v219, 0xffff0000, v154
	v_lshlrev_b32_e32 v220, 16, v155
	v_and_b32_e32 v221, 0xffff0000, v155
	v_mul_f32_e32 v214, 0xbfb8aa3b, v214
; __device__ __forceinline__ unsigned pk2(float lo, float hi) { f32x2 v = {lo, hi}; bf16x2_t b = __builtin_convertvector(v, bf16x2_t); return __builtin_bit_cast(unsigned, b); }
; __device__ __forceinline__ float bflo(unsigned w) { return __uint_as_float(w << 16); }
; __device__ __forceinline__ float bfhi(unsigned w) { return __uint_as_float(w & 0xffff0000u); }
; __device__ __forceinline__ float sigmoidf_(float x) { return __builtin_amdgcn_rcpf(1.0f + __builtin_amdgcn_exp2f(-x * LOG2E)); }
;     __device__ __forceinline__ void operator()(const f32x4 (&acc)[2][2][4][2], const Unit& u, int wr, int wc, int fr, int fq, LAS unsigned char* lds, int tid) const {
;     ...
;             for (int m = 0; m < 4; ++m) { const size_t row = (size_t)(row0 + ai * HALF + m * 16);
; #pragma unroll
;                 for (int bj = 0; bj < 2; ++bj) { const int col = col0 + bj * HALF; const u32x4 gw = gv[m][bj], pw = pv[m][bj];
;                     f32x4 z0, z1;
;                     z0[0] = sigmoidf_(bflo(gw.x)); z0[1] = sigmoidf_(bfhi(gw.x)); z0[2] = sigmoidf_(bflo(gw.y)); z0[3] = sigmoidf_(bfhi(gw.y));
;                     z1[0] = sigmoidf_(bflo(gw.z)); z1[1] = sigmoidf_(bfhi(gw.z)); z1[2] = sigmoidf_(bflo(gw.w)); z1[3] = sigmoidf_(bfhi(gw.w));
;                     const f32x4 q0 = {bflo(pw.x), bfhi(pw.x), bflo(pw.y), bfhi(pw.y)}, q1 = {bflo(pw.z), bfhi(pw.z), bflo(pw.w), bfhi(pw.w)};
;                     z0 = z0 * acc[ai][bj][m][0] + q0; z1 = z1 * acc[ai][bj][m][1] + q1;
;                     u32x4 w; w.x = pk2(z0[0], z0[1]); w.y = pk2(z0[2], z0[3]); w.z = pk2(z1[0], z1[1]); w.w = pk2(z1[2], z1[3]);
;                     *(gu32x4*)(dst + row * DM + col) = w; } }
	v_mul_f32_e32 v215, 0xbfb8aa3b, v215
	v_mul_f32_e32 v216, 0xbfb8aa3b, v216
	v_mul_f32_e32 v217, 0xbfb8aa3b, v217
	v_mul_f32_e32 v218, 0xbfb8aa3b, v218
	v_mul_f32_e32 v219, 0xbfb8aa3b, v219
	v_mul_f32_e32 v220, 0xbfb8aa3b, v220
	v_mul_f32_e32 v221, 0xbfb8aa3b, v221
	v_exp_f32_e32 v214, v214
	v_exp_f32_e32 v215, v215
	v_exp_f32_e32 v216, v216
	v_exp_f32_e32 v217, v217
	v_exp_f32_e32 v218, v218
	v_exp_f32_e32 v219, v219
	v_exp_f32_e32 v220, v220
	v_exp_f32_e32 v221, v221
	v_add_f32_e32 v214, 1.0, v214
	v_add_f32_e32 v215, 1.0, v215
	v_add_f32_e32 v216, 1.0, v216
	v_add_f32_e32 v217, 1.0, v217
	v_add_f32_e32 v218, 1.0, v218
	v_add_f32_e32 v219, 1.0, v219
	v_add_f32_e32 v220, 1.0, v220
	v_add_f32_e32 v221, 1.0, v221
	v_rcp_f32_e32 v214, v214
	v_rcp_f32_e32 v215, v215
	v_rcp_f32_e32 v216, v216
	v_rcp_f32_e32 v217, v217
	v_rcp_f32_e32 v218, v218
	v_rcp_f32_e32 v219, v219
	v_rcp_f32_e32 v220, v220
	v_rcp_f32_e32 v221, v221
	s_nop 0
	v_fma_f32 v102, v102, v214, 0
	v_fma_f32 v103, v103, v215, 0
	v_fma_f32 v104, v104, v216, 0
	v_fma_f32 v105, v105, v217, 0
	v_fma_f32 v98, v98, v218, 0
	v_fma_f32 v99, v99, v219, 0
	v_fma_f32 v100, v100, v220, 0
	v_fma_f32 v101, v101, v221, 0
	v_cvt_pk_bf16_f32 v152, v102, v103
	v_cvt_pk_bf16_f32 v153, v104, v105
	v_cvt_pk_bf16_f32 v154, v98, v99
	v_cvt_pk_bf16_f32 v155, v100, v101
	global_store_dwordx4 v123, v[148:151], s[16:17]
	global_store_dwordx4 v123, v[152:155], s[16:17] offset:256
	s_add_u32 s16, s16, 0x8000
	s_addc_u32 s17, s17, 0
	global_load_dwordx4 v[148:151], v122, s[0:1]
	global_load_dwordx4 v[152:155], v122, s[0:1] offset:256
	s_add_u32 s0, s0, 0x28000
	s_addc_u32 s1, s1, 0
	s_waitcnt vmcnt(10)
	v_lshlrev_b32_e32 v214, 16, v164
	v_and_b32_e32 v215, 0xffff0000, v164
	v_lshlrev_b32_e32 v216, 16, v165
	v_and_b32_e32 v217, 0xffff0000, v165
	v_lshlrev_b32_e32 v218, 16, v166
	v_and_b32_e32 v219, 0xffff0000, v166
	v_lshlrev_b32_e32 v220, 16, v167
	v_and_b32_e32 v221, 0xffff0000, v167
	v_mul_f32_e32 v214, 0xbfb8aa3b, v214
	v_mul_f32_e32 v215, 0xbfb8aa3b, v215
	v_mul_f32_e32 v216, 0xbfb8aa3b, v216
	v_mul_f32_e32 v217, 0xbfb8aa3b, v217
	v_mul_f32_e32 v218, 0xbfb8aa3b, v218
	v_mul_f32_e32 v219, 0xbfb8aa3b, v219
	v_mul_f32_e32 v220, 0xbfb8aa3b, v220
	v_mul_f32_e32 v221, 0xbfb8aa3b, v221
	v_exp_f32_e32 v214, v214
	v_exp_f32_e32 v215, v215
	v_exp_f32_e32 v216, v216
	v_exp_f32_e32 v217, v217
	v_exp_f32_e32 v218, v218
	v_exp_f32_e32 v219, v219
	v_exp_f32_e32 v220, v220
	v_exp_f32_e32 v221, v221
	v_add_f32_e32 v214, 1.0, v214
	v_add_f32_e32 v215, 1.0, v215
	v_add_f32_e32 v216, 1.0, v216
	v_add_f32_e32 v217, 1.0, v217
	v_add_f32_e32 v218, 1.0, v218
	v_add_f32_e32 v219, 1.0, v219
	v_add_f32_e32 v220, 1.0, v220
	v_add_f32_e32 v221, 1.0, v221
	v_rcp_f32_e32 v214, v214
	v_rcp_f32_e32 v215, v215
	v_rcp_f32_e32 v216, v216
	v_rcp_f32_e32 v217, v217
	v_rcp_f32_e32 v218, v218
	v_rcp_f32_e32 v219, v219
	v_rcp_f32_e32 v220, v220
	v_rcp_f32_e32 v221, v221
	s_nop 0
	v_fma_f32 v94, v94, v214, 0
	v_fma_f32 v95, v95, v215, 0
	v_fma_f32 v96, v96, v216, 0
	v_fma_f32 v97, v97, v217, 0
	v_fma_f32 v90, v90, v218, 0
	v_fma_f32 v91, v91, v219, 0
	v_fma_f32 v92, v92, v220, 0
	v_fma_f32 v93, v93, v221, 0
	v_cvt_pk_bf16_f32 v164, v94, v95
	v_cvt_pk_bf16_f32 v165, v96, v97
	v_cvt_pk_bf16_f32 v166, v90, v91
	v_cvt_pk_bf16_f32 v167, v92, v93
	v_lshlrev_b32_e32 v214, 16, v168
	v_and_b32_e32 v215, 0xffff0000, v168
	v_lshlrev_b32_e32 v216, 16, v169
	v_and_b32_e32 v217, 0xffff0000, v169
	v_lshlrev_b32_e32 v218, 16, v170
	v_and_b32_e32 v219, 0xffff0000, v170
	v_lshlrev_b32_e32 v220, 16, v171
	v_and_b32_e32 v221, 0xffff0000, v171
	v_mul_f32_e32 v214, 0xbfb8aa3b, v214
	v_mul_f32_e32 v215, 0xbfb8aa3b, v215
	v_mul_f32_e32 v216, 0xbfb8aa3b, v216
	v_mul_f32_e32 v217, 0xbfb8aa3b, v217
	v_mul_f32_e32 v218, 0xbfb8aa3b, v218
	v_mul_f32_e32 v219, 0xbfb8aa3b, v219
	v_mul_f32_e32 v220, 0xbfb8aa3b, v220
	v_mul_f32_e32 v221, 0xbfb8aa3b, v221
	v_exp_f32_e32 v214, v214
	v_exp_f32_e32 v215, v215
	v_exp_f32_e32 v216, v216
	v_exp_f32_e32 v217, v217
	v_exp_f32_e32 v218, v218
	v_exp_f32_e32 v219, v219
	v_exp_f32_e32 v220, v220
	v_exp_f32_e32 v221, v221
	v_add_f32_e32 v214, 1.0, v214
	v_add_f32_e32 v215, 1.0, v215
	v_add_f32_e32 v216, 1.0, v216
	v_add_f32_e32 v217, 1.0, v217
	v_add_f32_e32 v218, 1.0, v218
	v_add_f32_e32 v219, 1.0, v219
	v_add_f32_e32 v220, 1.0, v220
	v_add_f32_e32 v221, 1.0, v221
	v_rcp_f32_e32 v214, v214
	v_rcp_f32_e32 v215, v215
	v_rcp_f32_e32 v216, v216
	v_rcp_f32_e32 v217, v217
	v_rcp_f32_e32 v218, v218
	v_rcp_f32_e32 v219, v219
	v_rcp_f32_e32 v220, v220
	v_rcp_f32_e32 v221, v221
	s_nop 0
	v_fma_f32 v86, v86, v214, 0
	v_fma_f32 v87, v87, v215, 0
	v_fma_f32 v88, v88, v216, 0
	v_fma_f32 v89, v89, v217, 0
	v_fma_f32 v82, v82, v218, 0
	v_fma_f32 v83, v83, v219, 0
	v_fma_f32 v84, v84, v220, 0
	v_fma_f32 v85, v85, v221, 0
	v_cvt_pk_bf16_f32 v168, v86, v87
	v_cvt_pk_bf16_f32 v169, v88, v89
	v_cvt_pk_bf16_f32 v170, v82, v83
	v_cvt_pk_bf16_f32 v171, v84, v85
	global_store_dwordx4 v123, v[164:167], s[16:17]
	global_store_dwordx4 v123, v[168:171], s[16:17] offset:256
	s_add_u32 s16, s16, 0x8000
	s_addc_u32 s17, s17, 0
	global_load_dwordx4 v[164:167], v122, s[0:1]
	global_load_dwordx4 v[168:171], v122, s[0:1] offset:256
	s_add_u32 s0, s0, 0x28000
	s_addc_u32 s1, s1, 0
	s_waitcnt vmcnt(12)
; __device__ __forceinline__ unsigned pk2(float lo, float hi) { f32x2 v = {lo, hi}; bf16x2_t b = __builtin_convertvector(v, bf16x2_t); return __builtin_bit_cast(unsigned, b); }
; __device__ __forceinline__ float bflo(unsigned w) { return __uint_as_float(w << 16); }
; __device__ __forceinline__ float bfhi(unsigned w) { return __uint_as_float(w & 0xffff0000u); }
; __device__ __forceinline__ float sigmoidf_(float x) { return __builtin_amdgcn_rcpf(1.0f + __builtin_amdgcn_exp2f(-x * LOG2E)); }
;     __device__ __forceinline__ void operator()(const f32x4 (&acc)[2][2][4][2], const Unit& u, int wr, int wc, int fr, int fq, LAS unsigned char* lds, int tid) const {
;     ...
;             for (int m = 0; m < 4; ++m) { const size_t row = (size_t)(row0 + ai * HALF + m * 16);
; #pragma unroll
;                 for (int bj = 0; bj < 2; ++bj) { const int col = col0 + bj * HALF; const u32x4 gw = gv[m][bj], pw = pv[m][bj];
;                     f32x4 z0, z1;
;                     z0[0] = sigmoidf_(bflo(gw.x)); z0[1] = sigmoidf_(bfhi(gw.x)); z0[2] = sigmoidf_(bflo(gw.y)); z0[3] = sigmoidf_(bfhi(gw.y));
;                     z1[0] = sigmoidf_(bflo(gw.z)); z1[1] = sigmoidf_(bfhi(gw.z)); z1[2] = sigmoidf_(bflo(gw.w)); z1[3] = sigmoidf_(bfhi(gw.w));
;                     const f32x4 q0 = {bflo(pw.x), bfhi(pw.x), bflo(pw.y), bfhi(pw.y)}, q1 = {bflo(pw.z), bfhi(pw.z), bflo(pw.w), bfhi(pw.w)};
;                     z0 = z0 * acc[ai][bj][m][0] + q0; z1 = z1 * acc[ai][bj][m][1] + q1;
;                     u32x4 w; w.x = pk2(z0[0], z0[1]); w.y = pk2(z0[2], z0[3]); w.z = pk2(z1[0], z1[1]); w.w = pk2(z1[2], z1[3]);
;                     *(gu32x4*)(dst + row * DM + col) = w; } }
	v_lshlrev_b32_e32 v214, 16, v180
	v_and_b32_e32 v215, 0xffff0000, v180
	v_lshlrev_b32_e32 v216, 16, v181
	v_and_b32_e32 v217, 0xffff0000, v181
	v_lshlrev_b32_e32 v218, 16, v182
	v_and_b32_e32 v219, 0xffff0000, v182
	v_lshlrev_b32_e32 v220, 16, v183
	v_and_b32_e32 v221, 0xffff0000, v183
	v_mul_f32_e32 v214, 0xbfb8aa3b, v214
	v_mul_f32_e32 v215, 0xbfb8aa3b, v215
	v_mul_f32_e32 v216, 0xbfb8aa3b, v216
	v_mul_f32_e32 v217, 0xbfb8aa3b, v217
	v_mul_f32_e32 v218, 0xbfb8aa3b, v218
	v_mul_f32_e32 v219, 0xbfb8aa3b, v219
	v_mul_f32_e32 v220, 0xbfb8aa3b, v220
	v_mul_f32_e32 v221, 0xbfb8aa3b, v221
	v_exp_f32_e32 v214, v214
	v_exp_f32_e32 v215, v215
	v_exp_f32_e32 v216, v216
	v_exp_f32_e32 v217, v217
	v_exp_f32_e32 v218, v218
	v_exp_f32_e32 v219, v219
	v_exp_f32_e32 v220, v220
	v_exp_f32_e32 v221, v221
	v_add_f32_e32 v214, 1.0, v214
	v_add_f32_e32 v215, 1.0, v215
	v_add_f32_e32 v216, 1.0, v216
	v_add_f32_e32 v217, 1.0, v217
	v_add_f32_e32 v218, 1.0, v218
	v_add_f32_e32 v219, 1.0, v219
	v_add_f32_e32 v220, 1.0, v220
	v_add_f32_e32 v221, 1.0, v221
	v_rcp_f32_e32 v214, v214
	v_rcp_f32_e32 v215, v215
	v_rcp_f32_e32 v216, v216
	v_rcp_f32_e32 v217, v217
	v_rcp_f32_e32 v218, v218
	v_rcp_f32_e32 v219, v219
	v_rcp_f32_e32 v220, v220
	v_rcp_f32_e32 v221, v221
	s_nop 0
	v_fma_f32 v78, v78, v214, 0
	v_fma_f32 v79, v79, v215, 0
	v_fma_f32 v80, v80, v216, 0
	v_fma_f32 v81, v81, v217, 0
	v_fma_f32 v74, v74, v218, 0
	v_fma_f32 v75, v75, v219, 0
	v_fma_f32 v76, v76, v220, 0
	v_fma_f32 v77, v77, v221, 0
	v_cvt_pk_bf16_f32 v180, v78, v79
	v_cvt_pk_bf16_f32 v181, v80, v81
	v_cvt_pk_bf16_f32 v182, v74, v75
	v_cvt_pk_bf16_f32 v183, v76, v77
	v_lshlrev_b32_e32 v214, 16, v184
	v_and_b32_e32 v215, 0xffff0000, v184
	v_lshlrev_b32_e32 v216, 16, v185
	v_and_b32_e32 v217, 0xffff0000, v185
	v_lshlrev_b32_e32 v218, 16, v186
	v_and_b32_e32 v219, 0xffff0000, v186
	v_lshlrev_b32_e32 v220, 16, v187
	v_and_b32_e32 v221, 0xffff0000, v187
	v_mul_f32_e32 v214, 0xbfb8aa3b, v214
	v_mul_f32_e32 v215, 0xbfb8aa3b, v215
	v_mul_f32_e32 v216, 0xbfb8aa3b, v216
	v_mul_f32_e32 v217, 0xbfb8aa3b, v217
	v_mul_f32_e32 v218, 0xbfb8aa3b, v218
	v_mul_f32_e32 v219, 0xbfb8aa3b, v219
	v_mul_f32_e32 v220, 0xbfb8aa3b, v220
	v_mul_f32_e32 v221, 0xbfb8aa3b, v221
	v_exp_f32_e32 v214, v214
	v_exp_f32_e32 v215, v215
	v_exp_f32_e32 v216, v216
	v_exp_f32_e32 v217, v217
	v_exp_f32_e32 v218, v218
	v_exp_f32_e32 v219, v219
	v_exp_f32_e32 v220, v220
	v_exp_f32_e32 v221, v221
	v_add_f32_e32 v214, 1.0, v214
	v_add_f32_e32 v215, 1.0, v215
	v_add_f32_e32 v216, 1.0, v216
	v_add_f32_e32 v217, 1.0, v217
	v_add_f32_e32 v218, 1.0, v218
	v_add_f32_e32 v219, 1.0, v219
	v_add_f32_e32 v220, 1.0, v220
	v_add_f32_e32 v221, 1.0, v221
	v_rcp_f32_e32 v214, v214
	v_rcp_f32_e32 v215, v215
	v_rcp_f32_e32 v216, v216
	v_rcp_f32_e32 v217, v217
	v_rcp_f32_e32 v218, v218
	v_rcp_f32_e32 v219, v219
	v_rcp_f32_e32 v220, v220
	v_rcp_f32_e32 v221, v221
	s_nop 0
	v_fma_f32 v70, v70, v214, 0
	v_fma_f32 v71, v71, v215, 0
	v_fma_f32 v72, v72, v216, 0
	v_fma_f32 v73, v73, v217, 0
	v_fma_f32 v66, v66, v218, 0
	v_fma_f32 v67, v67, v219, 0
	v_fma_f32 v68, v68, v220, 0
	v_fma_f32 v69, v69, v221, 0
	v_cvt_pk_bf16_f32 v184, v70, v71
	v_cvt_pk_bf16_f32 v185, v72, v73
	v_cvt_pk_bf16_f32 v186, v66, v67
	v_cvt_pk_bf16_f32 v187, v68, v69
	global_store_dwordx4 v123, v[180:183], s[16:17]
	global_store_dwordx4 v123, v[184:187], s[16:17] offset:256
	s_add_u32 s16, s16, 0x28000
	s_addc_u32 s17, s17, 0
	global_load_dwordx4 v[180:183], v122, s[0:1]
	global_load_dwordx4 v[184:187], v122, s[0:1] offset:256
	s_add_u32 s0, s0, 0xc8000
	s_addc_u32 s1, s1, 0
	s_waitcnt vmcnt(12)
	v_lshlrev_b32_e32 v214, 16, v132
	v_and_b32_e32 v215, 0xffff0000, v132
	v_lshlrev_b32_e32 v216, 16, v133
	v_and_b32_e32 v217, 0xffff0000, v133
	v_lshlrev_b32_e32 v218, 16, v134
	v_and_b32_e32 v219, 0xffff0000, v134
	v_lshlrev_b32_e32 v220, 16, v135
	v_and_b32_e32 v221, 0xffff0000, v135
	v_mul_f32_e32 v214, 0xbfb8aa3b, v214
	v_mul_f32_e32 v215, 0xbfb8aa3b, v215
	v_mul_f32_e32 v216, 0xbfb8aa3b, v216
	v_mul_f32_e32 v217, 0xbfb8aa3b, v217
	v_mul_f32_e32 v218, 0xbfb8aa3b, v218
	v_mul_f32_e32 v219, 0xbfb8aa3b, v219
	v_mul_f32_e32 v220, 0xbfb8aa3b, v220
	v_mul_f32_e32 v221, 0xbfb8aa3b, v221
	v_exp_f32_e32 v214, v214
	v_exp_f32_e32 v215, v215
	v_exp_f32_e32 v216, v216
	v_exp_f32_e32 v217, v217
	v_exp_f32_e32 v218, v218
	v_exp_f32_e32 v219, v219
	v_exp_f32_e32 v220, v220
	v_exp_f32_e32 v221, v221
	v_add_f32_e32 v214, 1.0, v214
	v_add_f32_e32 v215, 1.0, v215
	v_add_f32_e32 v216, 1.0, v216
	v_add_f32_e32 v217, 1.0, v217
	v_add_f32_e32 v218, 1.0, v218
	v_add_f32_e32 v219, 1.0, v219
	v_add_f32_e32 v220, 1.0, v220
	v_add_f32_e32 v221, 1.0, v221
	v_rcp_f32_e32 v214, v214
	v_rcp_f32_e32 v215, v215
	v_rcp_f32_e32 v216, v216
	v_rcp_f32_e32 v217, v217
	v_rcp_f32_e32 v218, v218
	v_rcp_f32_e32 v219, v219
	v_rcp_f32_e32 v220, v220
	v_rcp_f32_e32 v221, v221
	s_nop 0
	v_fma_f32 v62, v62, v214, 0
	v_fma_f32 v63, v63, v215, 0
	v_fma_f32 v64, v64, v216, 0
	v_fma_f32 v65, v65, v217, 0
	v_fma_f32 v58, v58, v218, 0
	v_fma_f32 v59, v59, v219, 0
	v_fma_f32 v60, v60, v220, 0
	v_fma_f32 v61, v61, v221, 0
	v_cvt_pk_bf16_f32 v132, v62, v63
	v_cvt_pk_bf16_f32 v133, v64, v65
	v_cvt_pk_bf16_f32 v134, v58, v59
	v_cvt_pk_bf16_f32 v135, v60, v61
	v_lshlrev_b32_e32 v214, 16, v136
	v_and_b32_e32 v215, 0xffff0000, v136
	v_lshlrev_b32_e32 v216, 16, v137
	v_and_b32_e32 v217, 0xffff0000, v137
	v_lshlrev_b32_e32 v218, 16, v138
	v_and_b32_e32 v219, 0xffff0000, v138
	v_lshlrev_b32_e32 v220, 16, v139
	v_and_b32_e32 v221, 0xffff0000, v139
	v_mul_f32_e32 v214, 0xbfb8aa3b, v214
	v_mul_f32_e32 v215, 0xbfb8aa3b, v215
	v_mul_f32_e32 v216, 0xbfb8aa3b, v216
	v_mul_f32_e32 v217, 0xbfb8aa3b, v217
	v_mul_f32_e32 v218, 0xbfb8aa3b, v218
	v_mul_f32_e32 v219, 0xbfb8aa3b, v219
	v_mul_f32_e32 v220, 0xbfb8aa3b, v220
	v_mul_f32_e32 v221, 0xbfb8aa3b, v221
	v_exp_f32_e32 v214, v214
	v_exp_f32_e32 v215, v215
	v_exp_f32_e32 v216, v216
	v_exp_f32_e32 v217, v217
	v_exp_f32_e32 v218, v218
	v_exp_f32_e32 v219, v219
	v_exp_f32_e32 v220, v220
	v_exp_f32_e32 v221, v221
	v_add_f32_e32 v214, 1.0, v214
	v_add_f32_e32 v215, 1.0, v215
	v_add_f32_e32 v216, 1.0, v216
	v_add_f32_e32 v217, 1.0, v217
	v_add_f32_e32 v218, 1.0, v218
	v_add_f32_e32 v219, 1.0, v219
	v_add_f32_e32 v220, 1.0, v220
	v_add_f32_e32 v221, 1.0, v221
	v_rcp_f32_e32 v214, v214
	v_rcp_f32_e32 v215, v215
	v_rcp_f32_e32 v216, v216
	v_rcp_f32_e32 v217, v217
	v_rcp_f32_e32 v218, v218
	v_rcp_f32_e32 v219, v219
	v_rcp_f32_e32 v220, v220
	v_rcp_f32_e32 v221, v221
	s_nop 0
	v_fma_f32 v54, v54, v214, 0
	v_fma_f32 v55, v55, v215, 0
	v_fma_f32 v56, v56, v216, 0
	v_fma_f32 v57, v57, v217, 0
	v_fma_f32 v50, v50, v218, 0
	v_fma_f32 v51, v51, v219, 0
	v_fma_f32 v52, v52, v220, 0
	v_fma_f32 v53, v53, v221, 0
	v_cvt_pk_bf16_f32 v136, v54, v55
	v_cvt_pk_bf16_f32 v137, v56, v57
	v_cvt_pk_bf16_f32 v138, v50, v51
	v_cvt_pk_bf16_f32 v139, v52, v53
	global_store_dwordx4 v123, v[132:135], s[16:17]
	global_store_dwordx4 v123, v[136:139], s[16:17] offset:256
	s_add_u32 s16, s16, 0x8000
	s_addc_u32 s17, s17, 0
	s_waitcnt vmcnt(10)
; __device__ __forceinline__ unsigned pk2(float lo, float hi) { f32x2 v = {lo, hi}; bf16x2_t b = __builtin_convertvector(v, bf16x2_t); return __builtin_bit_cast(unsigned, b); }
; __device__ __forceinline__ float bflo(unsigned w) { return __uint_as_float(w << 16); }
; __device__ __forceinline__ float bfhi(unsigned w) { return __uint_as_float(w & 0xffff0000u); }
; __device__ __forceinline__ float sigmoidf_(float x) { return __builtin_amdgcn_rcpf(1.0f + __builtin_amdgcn_exp2f(-x * LOG2E)); }
;     __device__ __forceinline__ void operator()(const f32x4 (&acc)[2][2][4][2], const Unit& u, int wr, int wc, int fr, int fq, LAS unsigned char* lds, int tid) const {
;     ...
;             for (int m = 0; m < 4; ++m) { const size_t row = (size_t)(row0 + ai * HALF + m * 16);
; #pragma unroll
;                 for (int bj = 0; bj < 2; ++bj) { const int col = col0 + bj * HALF; const u32x4 gw = gv[m][bj], pw = pv[m][bj];
;                     f32x4 z0, z1;
;                     z0[0] = sigmoidf_(bflo(gw.x)); z0[1] = sigmoidf_(bfhi(gw.x)); z0[2] = sigmoidf_(bflo(gw.y)); z0[3] = sigmoidf_(bfhi(gw.y));
;                     z1[0] = sigmoidf_(bflo(gw.z)); z1[1] = sigmoidf_(bfhi(gw.z)); z1[2] = sigmoidf_(bflo(gw.w)); z1[3] = sigmoidf_(bfhi(gw.w));
;                     const f32x4 q0 = {bflo(pw.x), bfhi(pw.x), bflo(pw.y), bfhi(pw.y)}, q1 = {bflo(pw.z), bfhi(pw.z), bflo(pw.w), bfhi(pw.w)};
;                     z0 = z0 * acc[ai][bj][m][0] + q0; z1 = z1 * acc[ai][bj][m][1] + q1;
;                     u32x4 w; w.x = pk2(z0[0], z0[1]); w.y = pk2(z0[2], z0[3]); w.z = pk2(z1[0], z1[1]); w.w = pk2(z1[2], z1[3]);
;                     *(gu32x4*)(dst + row * DM + col) = w; } }
	v_lshlrev_b32_e32 v214, 16, v148
	v_and_b32_e32 v215, 0xffff0000, v148
	v_lshlrev_b32_e32 v216, 16, v149
	v_and_b32_e32 v217, 0xffff0000, v149
	v_lshlrev_b32_e32 v218, 16, v150
	v_and_b32_e32 v219, 0xffff0000, v150
	v_lshlrev_b32_e32 v220, 16, v151
	v_and_b32_e32 v221, 0xffff0000, v151
	v_mul_f32_e32 v214, 0xbfb8aa3b, v214
	v_mul_f32_e32 v215, 0xbfb8aa3b, v215
	v_mul_f32_e32 v216, 0xbfb8aa3b, v216
	v_mul_f32_e32 v217, 0xbfb8aa3b, v217
	v_mul_f32_e32 v218, 0xbfb8aa3b, v218
	v_mul_f32_e32 v219, 0xbfb8aa3b, v219
	v_mul_f32_e32 v220, 0xbfb8aa3b, v220
	v_mul_f32_e32 v221, 0xbfb8aa3b, v221
	v_exp_f32_e32 v214, v214
	v_exp_f32_e32 v215, v215
	v_exp_f32_e32 v216, v216
	v_exp_f32_e32 v217, v217
	v_exp_f32_e32 v218, v218
	v_exp_f32_e32 v219, v219
	v_exp_f32_e32 v220, v220
	v_exp_f32_e32 v221, v221
	v_add_f32_e32 v214, 1.0, v214
	v_add_f32_e32 v215, 1.0, v215
	v_add_f32_e32 v216, 1.0, v216
	v_add_f32_e32 v217, 1.0, v217
	v_add_f32_e32 v218, 1.0, v218
	v_add_f32_e32 v219, 1.0, v219
	v_add_f32_e32 v220, 1.0, v220
	v_add_f32_e32 v221, 1.0, v221
	v_rcp_f32_e32 v214, v214
	v_rcp_f32_e32 v215, v215
	v_rcp_f32_e32 v216, v216
	v_rcp_f32_e32 v217, v217
	v_rcp_f32_e32 v218, v218
	v_rcp_f32_e32 v219, v219
	v_rcp_f32_e32 v220, v220
	v_rcp_f32_e32 v221, v221
	s_nop 0
	v_fma_f32 v46, v46, v214, 0
	v_fma_f32 v47, v47, v215, 0
	v_fma_f32 v48, v48, v216, 0
	v_fma_f32 v49, v49, v217, 0
	v_fma_f32 v42, v42, v218, 0
	v_fma_f32 v43, v43, v219, 0
	v_fma_f32 v44, v44, v220, 0
	v_fma_f32 v45, v45, v221, 0
	v_cvt_pk_bf16_f32 v148, v46, v47
	v_cvt_pk_bf16_f32 v149, v48, v49
	v_cvt_pk_bf16_f32 v150, v42, v43
	v_cvt_pk_bf16_f32 v151, v44, v45
	v_lshlrev_b32_e32 v214, 16, v152
	v_and_b32_e32 v215, 0xffff0000, v152
	v_lshlrev_b32_e32 v216, 16, v153
	v_and_b32_e32 v217, 0xffff0000, v153
	v_lshlrev_b32_e32 v218, 16, v154
	v_and_b32_e32 v219, 0xffff0000, v154
	v_lshlrev_b32_e32 v220, 16, v155
	v_and_b32_e32 v221, 0xffff0000, v155
	v_mul_f32_e32 v214, 0xbfb8aa3b, v214
	v_mul_f32_e32 v215, 0xbfb8aa3b, v215
	v_mul_f32_e32 v216, 0xbfb8aa3b, v216
	v_mul_f32_e32 v217, 0xbfb8aa3b, v217
	v_mul_f32_e32 v218, 0xbfb8aa3b, v218
	v_mul_f32_e32 v219, 0xbfb8aa3b, v219
	v_mul_f32_e32 v220, 0xbfb8aa3b, v220
	v_mul_f32_e32 v221, 0xbfb8aa3b, v221
	v_exp_f32_e32 v214, v214
	v_exp_f32_e32 v215, v215
	v_exp_f32_e32 v216, v216
	v_exp_f32_e32 v217, v217
	v_exp_f32_e32 v218, v218
	v_exp_f32_e32 v219, v219
	v_exp_f32_e32 v220, v220
	v_exp_f32_e32 v221, v221
	v_add_f32_e32 v214, 1.0, v214
	v_add_f32_e32 v215, 1.0, v215
	v_add_f32_e32 v216, 1.0, v216
	v_add_f32_e32 v217, 1.0, v217
	v_add_f32_e32 v218, 1.0, v218
	v_add_f32_e32 v219, 1.0, v219
	v_add_f32_e32 v220, 1.0, v220
	v_add_f32_e32 v221, 1.0, v221
	v_rcp_f32_e32 v214, v214
	v_rcp_f32_e32 v215, v215
	v_rcp_f32_e32 v216, v216
	v_rcp_f32_e32 v217, v217
	v_rcp_f32_e32 v218, v218
	v_rcp_f32_e32 v219, v219
	v_rcp_f32_e32 v220, v220
	v_rcp_f32_e32 v221, v221
	s_nop 0
	v_fma_f32 v38, v38, v214, 0
	v_fma_f32 v39, v39, v215, 0
	v_fma_f32 v40, v40, v216, 0
	v_fma_f32 v41, v41, v217, 0
	v_fma_f32 v34, v34, v218, 0
	v_fma_f32 v35, v35, v219, 0
	v_fma_f32 v36, v36, v220, 0
	v_fma_f32 v37, v37, v221, 0
	v_cvt_pk_bf16_f32 v152, v38, v39
	v_cvt_pk_bf16_f32 v153, v40, v41
	v_cvt_pk_bf16_f32 v154, v34, v35
	v_cvt_pk_bf16_f32 v155, v36, v37
	global_store_dwordx4 v123, v[148:151], s[16:17]
	global_store_dwordx4 v123, v[152:155], s[16:17] offset:256
	s_add_u32 s16, s16, 0x8000
	s_addc_u32 s17, s17, 0
	s_waitcnt vmcnt(8)
	v_lshlrev_b32_e32 v214, 16, v164
	v_and_b32_e32 v215, 0xffff0000, v164
	v_lshlrev_b32_e32 v216, 16, v165
	v_and_b32_e32 v217, 0xffff0000, v165
	v_lshlrev_b32_e32 v218, 16, v166
	v_and_b32_e32 v219, 0xffff0000, v166
	v_lshlrev_b32_e32 v220, 16, v167
	v_and_b32_e32 v221, 0xffff0000, v167
	v_mul_f32_e32 v214, 0xbfb8aa3b, v214
	v_mul_f32_e32 v215, 0xbfb8aa3b, v215
	v_mul_f32_e32 v216, 0xbfb8aa3b, v216
	v_mul_f32_e32 v217, 0xbfb8aa3b, v217
	v_mul_f32_e32 v218, 0xbfb8aa3b, v218
	v_mul_f32_e32 v219, 0xbfb8aa3b, v219
	v_mul_f32_e32 v220, 0xbfb8aa3b, v220
	v_mul_f32_e32 v221, 0xbfb8aa3b, v221
	v_exp_f32_e32 v214, v214
	v_exp_f32_e32 v215, v215
	v_exp_f32_e32 v216, v216
	v_exp_f32_e32 v217, v217
	v_exp_f32_e32 v218, v218
	v_exp_f32_e32 v219, v219
	v_exp_f32_e32 v220, v220
	v_exp_f32_e32 v221, v221
	v_add_f32_e32 v214, 1.0, v214
	v_add_f32_e32 v215, 1.0, v215
	v_add_f32_e32 v216, 1.0, v216
	v_add_f32_e32 v217, 1.0, v217
	v_add_f32_e32 v218, 1.0, v218
	v_add_f32_e32 v219, 1.0, v219
	v_add_f32_e32 v220, 1.0, v220
	v_add_f32_e32 v221, 1.0, v221
	v_rcp_f32_e32 v214, v214
	v_rcp_f32_e32 v215, v215
	v_rcp_f32_e32 v216, v216
	v_rcp_f32_e32 v217, v217
	v_rcp_f32_e32 v218, v218
	v_rcp_f32_e32 v219, v219
	v_rcp_f32_e32 v220, v220
	v_rcp_f32_e32 v221, v221
	s_nop 0
	v_fma_f32 v30, v30, v214, 0
	v_fma_f32 v31, v31, v215, 0
	v_fma_f32 v32, v32, v216, 0
	v_fma_f32 v33, v33, v217, 0
	v_fma_f32 v26, v26, v218, 0
	v_fma_f32 v27, v27, v219, 0
	v_fma_f32 v28, v28, v220, 0
	v_fma_f32 v29, v29, v221, 0
	v_cvt_pk_bf16_f32 v164, v30, v31
	v_cvt_pk_bf16_f32 v165, v32, v33
	v_cvt_pk_bf16_f32 v166, v26, v27
	v_cvt_pk_bf16_f32 v167, v28, v29
	v_lshlrev_b32_e32 v214, 16, v168
	v_and_b32_e32 v215, 0xffff0000, v168
	v_lshlrev_b32_e32 v216, 16, v169
	v_and_b32_e32 v217, 0xffff0000, v169
	v_lshlrev_b32_e32 v218, 16, v170
	v_and_b32_e32 v219, 0xffff0000, v170
	v_lshlrev_b32_e32 v220, 16, v171
	v_and_b32_e32 v221, 0xffff0000, v171
	v_mul_f32_e32 v214, 0xbfb8aa3b, v214
	v_mul_f32_e32 v215, 0xbfb8aa3b, v215
	v_mul_f32_e32 v216, 0xbfb8aa3b, v216
	v_mul_f32_e32 v217, 0xbfb8aa3b, v217
	v_mul_f32_e32 v218, 0xbfb8aa3b, v218
	v_mul_f32_e32 v219, 0xbfb8aa3b, v219
	v_mul_f32_e32 v220, 0xbfb8aa3b, v220
	v_mul_f32_e32 v221, 0xbfb8aa3b, v221
	v_exp_f32_e32 v214, v214
	v_exp_f32_e32 v215, v215
	v_exp_f32_e32 v216, v216
	v_exp_f32_e32 v217, v217
	v_exp_f32_e32 v218, v218
	v_exp_f32_e32 v219, v219
	v_exp_f32_e32 v220, v220
	v_exp_f32_e32 v221, v221
	v_add_f32_e32 v214, 1.0, v214
	v_add_f32_e32 v215, 1.0, v215
	v_add_f32_e32 v216, 1.0, v216
	v_add_f32_e32 v217, 1.0, v217
	v_add_f32_e32 v218, 1.0, v218
	v_add_f32_e32 v219, 1.0, v219
	v_add_f32_e32 v220, 1.0, v220
	v_add_f32_e32 v221, 1.0, v221
	v_rcp_f32_e32 v214, v214
	v_rcp_f32_e32 v215, v215
	v_rcp_f32_e32 v216, v216
	v_rcp_f32_e32 v217, v217
	v_rcp_f32_e32 v218, v218
	v_rcp_f32_e32 v219, v219
	v_rcp_f32_e32 v220, v220
	v_rcp_f32_e32 v221, v221
	s_nop 0
	v_fma_f32 v22, v22, v214, 0
	v_fma_f32 v23, v23, v215, 0
	v_fma_f32 v24, v24, v216, 0
	v_fma_f32 v25, v25, v217, 0
	v_fma_f32 v18, v18, v218, 0
	v_fma_f32 v19, v19, v219, 0
	v_fma_f32 v20, v20, v220, 0
	v_fma_f32 v21, v21, v221, 0
	v_cvt_pk_bf16_f32 v168, v22, v23
	v_cvt_pk_bf16_f32 v169, v24, v25
	v_cvt_pk_bf16_f32 v170, v18, v19
	v_cvt_pk_bf16_f32 v171, v20, v21
	global_store_dwordx4 v123, v[164:167], s[16:17]
	global_store_dwordx4 v123, v[168:171], s[16:17] offset:256
	s_add_u32 s16, s16, 0x8000
	s_addc_u32 s17, s17, 0
	s_waitcnt vmcnt(6)
; __device__ __forceinline__ unsigned pk2(float lo, float hi) { f32x2 v = {lo, hi}; bf16x2_t b = __builtin_convertvector(v, bf16x2_t); return __builtin_bit_cast(unsigned, b); }
; __device__ __forceinline__ float bflo(unsigned w) { return __uint_as_float(w << 16); }
; __device__ __forceinline__ float bfhi(unsigned w) { return __uint_as_float(w & 0xffff0000u); }
; __device__ __forceinline__ float sigmoidf_(float x) { return __builtin_amdgcn_rcpf(1.0f + __builtin_amdgcn_exp2f(-x * LOG2E)); }
;     __device__ __forceinline__ void operator()(const f32x4 (&acc)[2][2][4][2], const Unit& u, int wr, int wc, int fr, int fq, LAS unsigned char* lds, int tid) const {
;     ...
;             for (int m = 0; m < 4; ++m) { const size_t row = (size_t)(row0 + ai * HALF + m * 16);
; #pragma unroll
;                 for (int bj = 0; bj < 2; ++bj) { const int col = col0 + bj * HALF; const u32x4 gw = gv[m][bj], pw = pv[m][bj];
;                     f32x4 z0, z1;
;                     z0[0] = sigmoidf_(bflo(gw.x)); z0[1] = sigmoidf_(bfhi(gw.x)); z0[2] = sigmoidf_(bflo(gw.y)); z0[3] = sigmoidf_(bfhi(gw.y));
;                     z1[0] = sigmoidf_(bflo(gw.z)); z1[1] = sigmoidf_(bfhi(gw.z)); z1[2] = sigmoidf_(bflo(gw.w)); z1[3] = sigmoidf_(bfhi(gw.w));
;                     const f32x4 q0 = {bflo(pw.x), bfhi(pw.x), bflo(pw.y), bfhi(pw.y)}, q1 = {bflo(pw.z), bfhi(pw.z), bflo(pw.w), bfhi(pw.w)};
;                     z0 = z0 * acc[ai][bj][m][0] + q0; z1 = z1 * acc[ai][bj][m][1] + q1;
;                     u32x4 w; w.x = pk2(z0[0], z0[1]); w.y = pk2(z0[2], z0[3]); w.z = pk2(z1[0], z1[1]); w.w = pk2(z1[2], z1[3]);
;                     *(gu32x4*)(dst + row * DM + col) = w; } }
	v_lshlrev_b32_e32 v214, 16, v180
	v_and_b32_e32 v215, 0xffff0000, v180
	v_lshlrev_b32_e32 v216, 16, v181
	v_and_b32_e32 v217, 0xffff0000, v181
	v_lshlrev_b32_e32 v218, 16, v182
	v_and_b32_e32 v219, 0xffff0000, v182
	v_lshlrev_b32_e32 v220, 16, v183
	v_and_b32_e32 v221, 0xffff0000, v183
	v_mul_f32_e32 v214, 0xbfb8aa3b, v214
	v_mul_f32_e32 v215, 0xbfb8aa3b, v215
	v_mul_f32_e32 v216, 0xbfb8aa3b, v216
	v_mul_f32_e32 v217, 0xbfb8aa3b, v217
	v_mul_f32_e32 v218, 0xbfb8aa3b, v218
	v_mul_f32_e32 v219, 0xbfb8aa3b, v219
	v_mul_f32_e32 v220, 0xbfb8aa3b, v220
	v_mul_f32_e32 v221, 0xbfb8aa3b, v221
	v_exp_f32_e32 v214, v214
	v_exp_f32_e32 v215, v215
	v_exp_f32_e32 v216, v216
	v_exp_f32_e32 v217, v217
	v_exp_f32_e32 v218, v218
	v_exp_f32_e32 v219, v219
	v_exp_f32_e32 v220, v220
	v_exp_f32_e32 v221, v221
	v_add_f32_e32 v214, 1.0, v214
	v_add_f32_e32 v215, 1.0, v215
	v_add_f32_e32 v216, 1.0, v216
	v_add_f32_e32 v217, 1.0, v217
	v_add_f32_e32 v218, 1.0, v218
	v_add_f32_e32 v219, 1.0, v219
	v_add_f32_e32 v220, 1.0, v220
	v_add_f32_e32 v221, 1.0, v221
	v_rcp_f32_e32 v214, v214
	v_rcp_f32_e32 v215, v215
	v_rcp_f32_e32 v216, v216
	v_rcp_f32_e32 v217, v217
	v_rcp_f32_e32 v218, v218
	v_rcp_f32_e32 v219, v219
	v_rcp_f32_e32 v220, v220
	v_rcp_f32_e32 v221, v221
	s_nop 0
	v_fma_f32 v14, v14, v214, 0
	v_fma_f32 v15, v15, v215, 0
	v_fma_f32 v16, v16, v216, 0
	v_fma_f32 v17, v17, v217, 0
	v_fma_f32 v10, v10, v218, 0
	v_fma_f32 v11, v11, v219, 0
	v_fma_f32 v12, v12, v220, 0
	v_fma_f32 v13, v13, v221, 0
	v_cvt_pk_bf16_f32 v180, v14, v15
	v_cvt_pk_bf16_f32 v181, v16, v17
	v_cvt_pk_bf16_f32 v182, v10, v11
	v_cvt_pk_bf16_f32 v183, v12, v13
	v_lshlrev_b32_e32 v214, 16, v184
	v_and_b32_e32 v215, 0xffff0000, v184
	v_lshlrev_b32_e32 v216, 16, v185
	v_and_b32_e32 v217, 0xffff0000, v185
	v_lshlrev_b32_e32 v218, 16, v186
	v_and_b32_e32 v219, 0xffff0000, v186
	v_lshlrev_b32_e32 v220, 16, v187
	v_and_b32_e32 v221, 0xffff0000, v187
	v_mul_f32_e32 v214, 0xbfb8aa3b, v214
	v_mul_f32_e32 v215, 0xbfb8aa3b, v215
	v_mul_f32_e32 v216, 0xbfb8aa3b, v216
	v_mul_f32_e32 v217, 0xbfb8aa3b, v217
	v_mul_f32_e32 v218, 0xbfb8aa3b, v218
	v_mul_f32_e32 v219, 0xbfb8aa3b, v219
	v_mul_f32_e32 v220, 0xbfb8aa3b, v220
	v_mul_f32_e32 v221, 0xbfb8aa3b, v221
	v_exp_f32_e32 v214, v214
	v_exp_f32_e32 v215, v215
	v_exp_f32_e32 v216, v216
	v_exp_f32_e32 v217, v217
	v_exp_f32_e32 v218, v218
	v_exp_f32_e32 v219, v219
	v_exp_f32_e32 v220, v220
	v_exp_f32_e32 v221, v221
	v_add_f32_e32 v214, 1.0, v214
	v_add_f32_e32 v215, 1.0, v215
	v_add_f32_e32 v216, 1.0, v216
	v_add_f32_e32 v217, 1.0, v217
	v_add_f32_e32 v218, 1.0, v218
	v_add_f32_e32 v219, 1.0, v219
	v_add_f32_e32 v220, 1.0, v220
	v_add_f32_e32 v221, 1.0, v221
	v_rcp_f32_e32 v214, v214
	v_rcp_f32_e32 v215, v215
	v_rcp_f32_e32 v216, v216
	v_rcp_f32_e32 v217, v217
	v_rcp_f32_e32 v218, v218
	v_rcp_f32_e32 v219, v219
	v_rcp_f32_e32 v220, v220
	v_rcp_f32_e32 v221, v221
	s_nop 0
	v_fma_f32 v6, v6, v214, 0
	v_fma_f32 v7, v7, v215, 0
	v_fma_f32 v8, v8, v216, 0
	v_fma_f32 v9, v9, v217, 0
	v_fma_f32 v2, v2, v218, 0
	v_fma_f32 v3, v3, v219, 0
	v_fma_f32 v4, v4, v220, 0
	v_fma_f32 v5, v5, v221, 0
	v_cvt_pk_bf16_f32 v184, v6, v7
	v_cvt_pk_bf16_f32 v185, v8, v9
	v_cvt_pk_bf16_f32 v186, v2, v3
	v_cvt_pk_bf16_f32 v187, v4, v5
	global_store_dwordx4 v123, v[180:183], s[16:17]
	global_store_dwordx4 v123, v[184:187], s[16:17] offset:256
	s_add_u32 s16, s16, 0x28000
	s_addc_u32 s17, s17, 0
.Lgate_done:
	s_andn2_b64 vcc, exec, s[2:3]
	s_mov_b64 s[0:1], -1
	s_cbranch_vccnz .LBB0_436
	s_andn2_b64 vcc, exec, s[6:7]
	s_cbranch_vccnz .LBB0_435
	s_barrier
	s_branch .LBB0_435
